# P5 stage 2: the 64 packed fp32 ops per head (v_pk_mul/add/fma_f32) split into scalar pairs (bit-identical); on top of all13
# baseline (speedup 1.0000x reference)
; #define LAS __attribute__((address_space(3)))
; #define LBAR() asm volatile("s_waitcnt lgkmcnt(0)\n\ts_barrier" ::: "memory")
; __device__ __forceinline__ void rwkv_chunk_group(Frame& F, int bc, unsigned long long& tsub) {
;     ...
;         asm volatile("s_waitcnt vmcnt(0)" ::: "memory"); LBAR();
;         f32x4 aw[2], aa[2], ag[2];
; #pragma unroll
;         for (int q = 0; q < 2; ++q) { const int n0 = 16 * ((2 * w + q) & 3); aw[q] = Z4; aa[q] = Z4; ag[q] = Z4;
;             const LAS unsigned char* wp = L + L_LWA + (n0 + fr) * 128 + fq * 16; const LAS unsigned char* gp = L + L_LG + (n0 + fr) * 64 + fq * 16;
; #pragma unroll
;             for (int k = 0; k < 2; ++k) { aw[q] = __builtin_amdgcn_mfma_f32_16x16x32_bf16(xw[k], *(const LAS bf16x8*)(wp + k * 64), aw[q], 0, 0, 0); aa[q] = __builtin_amdgcn_mfma_f32_16x16x32_bf16(xa[k], *(const LAS bf16x8*)(wp + 8192 + k * 64), aa[q], 0, 0, 0); }
; #pragma unroll
;             for (int k = 0; k < 5; ++k) ag[q] = __builtin_amdgcn_mfma_f32_16x16x32_bf16(xg[k], *(const LAS bf16x8*)(gp + k * 4096), ag[q], 0, 0, 0);
;     ...
;         const float mur = mu[gc], muk = mu[512 + gc], muv = mu[1024 + gc];
;         const float w0 = (PRM + 2048)[gc], a0 = (PRM + 2560)[gc], k_k = (PRM + 3072)[gc], k_a = (PRM + 3584)[gc], r_k = (PRM + 4096)[gc];
.LBB0_1412:
	s_waitcnt vmcnt(8)
	v_perm_b32 v160, v203, v202, s5
	v_perm_b32 v161, v216, v215, s5
	v_perm_b32 v166, v204, v203, s5
	v_perm_b32 v167, v217, v216, s5
	v_perm_b32 v168, v206, v205, s5
	v_perm_b32 v169, v219, v218, s5
	v_perm_b32 v170, v212, v207, s5
	v_perm_b32 v171, v221, v220, s5
	v_perm_b32 v165, v214, v213, s5
	v_perm_b32 v172, v223, v222, s5
	v_readlane_b32 s98, v254, 2
	v_readlane_b32 s100, v254, 20
	v_readlane_b32 s101, v254, 21
	s_add_i32 s98, s98, s12
	s_lshl_b32 s98, s98, 6
	s_and_b32 s98, s98, 0x1c0
	v_add_lshl_u32 v238, v208, s98, 2
	v_mov_b32_e32 v239, 0
	s_nop 0
	v_lshl_add_u64 v[232:233], s[100:101], 0, v[238:239]
	s_mov_b64 s[100:101], 0x2000
	v_lshl_add_u64 v[234:235], v[232:233], 0, s[100:101]
	s_mov_b64 s[100:101], 0x3800
	v_lshl_add_u64 v[236:237], v[232:233], 0, s[100:101]
	global_load_dword v224, v[232:233], off
	global_load_dword v225, v[232:233], off offset:2048
	global_load_dword v226, v[234:235], off offset:-4096
	global_load_dword v227, v[234:235], off
	global_load_dword v228, v[234:235], off offset:2048
	global_load_dword v229, v[236:237], off offset:-2048
	global_load_dword v230, v[236:237], off
	global_load_dword v231, v[236:237], off offset:2048
	s_waitcnt lgkmcnt(0)
	s_barrier
	v_xor_b32_e32 v102, 64, v137
	v_xor_b32_e32 v103, 64, v139
	ds_read_b128 v[36:39], v137
	ds_read_b128 v[76:79], v139
	ds_read_b128 v[98:101], v102
	ds_read_b128 v[174:177], v103
	ds_read_b128 v[40:43], v137 offset:8192
	ds_read_b128 v[80:83], v139 offset:8192
	ds_read_b128 v[178:181], v102 offset:8192
	ds_read_b128 v[182:185], v103 offset:8192
	ds_read_b128 v[44:47], v138
	ds_read_b128 v[84:87], v140
	ds_read_b128 v[186:189], v138 offset:4096
	ds_read_b128 v[232:235], v140 offset:4096
	ds_read_b128 v[236:239], v138 offset:8192
	ds_read_b128 v[240:243], v140 offset:8192
	ds_read_b128 v[244:247], v138 offset:12288
	s_waitcnt lgkmcnt(14)
	v_mfma_f32_16x16x32_bf16 v[36:39], v[0:3], v[36:39], 0
	ds_read_b128 v[248:251], v140 offset:12288
	v_add_u32_e32 v52, s33, v111
	s_mov_b32 s68, s12
	s_waitcnt lgkmcnt(14)
	v_mfma_f32_16x16x32_bf16 v[76:79], v[0:3], v[76:79], 0
	ds_read_b128 v[88:91], v138 offset:16384
	v_readlane_b32 s12, v254, 2
	s_add_i32 s14, s68, s12
	s_waitcnt lgkmcnt(14)
	v_mfma_f32_16x16x32_bf16 v[36:39], v[4:7], v[98:101], v[36:39]
	ds_read_b128 v[98:101], v140 offset:16384
	s_lshl_b32 s14, s14, 6
	s_waitcnt lgkmcnt(14)
	v_mfma_f32_16x16x32_bf16 v[76:79], v[4:7], v[174:177], v[76:79]
	s_and_b32 s14, s14, 0x1c0
	s_waitcnt lgkmcnt(13)
	v_mfma_f32_16x16x32_bf16 v[40:43], v[8:11], v[40:43], 0
	s_add_i32 s66, s11, s14
	s_waitcnt lgkmcnt(12)
	v_mfma_f32_16x16x32_bf16 v[80:83], v[8:11], v[80:83], 0
	v_add_u32_e32 v191, s6, v125
	s_waitcnt lgkmcnt(11)
	v_mfma_f32_16x16x32_bf16 v[40:43], v[12:15], v[178:181], v[40:43]

; #define LAS __attribute__((address_space(3)))
; #define LBAR() asm volatile("s_waitcnt lgkmcnt(0)\n\ts_barrier" ::: "memory")
; __device__ __forceinline__ void rwkv_chunk_group(Frame& F, int bc, unsigned long long& tsub) {
;     ...
;             for (int k = 0; k < 2; ++k) { aw[q] = __builtin_amdgcn_mfma_f32_16x16x32_bf16(xw[k], *(const LAS bf16x8*)(wp + k * 64), aw[q], 0, 0, 0); aa[q] = __builtin_amdgcn_mfma_f32_16x16x32_bf16(xa[k], *(const LAS bf16x8*)(wp + 8192 + k * 64), aa[q], 0, 0, 0); }
; #pragma unroll
;             for (int k = 0; k < 5; ++k) ag[q] = __builtin_amdgcn_mfma_f32_16x16x32_bf16(xg[k], *(const LAS bf16x8*)(gp + k * 4096), ag[q], 0, 0, 0);
;         }
;         LBAR();
; #pragma unroll
;         for (int q = 0; q < 2; ++q) { const int tw = 2 * w + q, m0 = 16 * (tw >> 2), n0 = 16 * (tw & 3);
; #pragma unroll
;             for (int v = 0; v < 4; ++v) { const int t = m0 + 4 * fq + v, cc = n0 + fr;
;                 *(LAS float*)(L + L_WL + (t * 65 + cc) * 4) = aw[q][v]; *(LAS float*)(L + L_AL + (t * 65 + cc) * 4) = aa[q][v]; *(LAS float*)(L + L_GL + (t * 65 + cc) * 4) = ag[q][v]; } }
	s_waitcnt lgkmcnt(10)
	v_mfma_f32_16x16x32_bf16 v[80:83], v[12:15], v[182:185], v[80:83]
	s_mov_b32 s64, s12
	s_waitcnt lgkmcnt(9)
	v_mfma_f32_16x16x32_bf16 v[44:47], v[16:19], v[44:47], 0
	s_add_i32 s12, s68, 1
	s_waitcnt lgkmcnt(8)
	v_mfma_f32_16x16x32_bf16 v[84:87], v[16:19], v[84:87], 0
	s_add_i32 s13, s12, s64
	s_waitcnt lgkmcnt(7)
	v_mfma_f32_16x16x32_bf16 v[44:47], v[20:23], v[186:189], v[44:47]
	v_add_u32_e32 v96, s6, v124
	s_waitcnt lgkmcnt(6)
	v_mfma_f32_16x16x32_bf16 v[84:87], v[20:23], v[232:235], v[84:87]
	v_add_u32_e32 v93, s7, v123
	s_waitcnt lgkmcnt(5)
	v_mfma_f32_16x16x32_bf16 v[44:47], v[24:27], v[236:239], v[44:47]
	v_add_u32_e32 v97, s7, v124
	s_waitcnt lgkmcnt(4)
	v_mfma_f32_16x16x32_bf16 v[84:87], v[24:27], v[240:243], v[84:87]
	v_add_u32_e32 v192, s7, v125
	s_waitcnt lgkmcnt(3)
	v_mfma_f32_16x16x32_bf16 v[44:47], v[28:31], v[244:247], v[44:47]
	v_lshlrev_b32_e32 v197, 16, v162
	s_waitcnt lgkmcnt(2)
	v_mfma_f32_16x16x32_bf16 v[84:87], v[28:31], v[248:251], v[84:87]
	v_and_b32_e32 v199, 0xffff0000, v172
	s_waitcnt lgkmcnt(1)
	v_mfma_f32_16x16x32_bf16 v[44:47], v[32:35], v[88:91], v[44:47]
	s_ashr_i32 s67, s66, 31
	s_waitcnt lgkmcnt(0)
	v_mfma_f32_16x16x32_bf16 v[84:87], v[32:35], v[98:101], v[84:87]
	s_and_b32 s13, s13, 7
	s_nop 7
	s_nop 7
	s_waitcnt lgkmcnt(0)
	s_barrier
	ds_write_b32 v52, v36
	v_add_u32_e32 v36, s6, v111
	ds_write_b32 v36, v40
	v_add_u32_e32 v36, s7, v111
	ds_write_b32 v36, v44
	v_add_u32_e32 v36, s33, v112
	ds_write_b32 v36, v37
	v_add_u32_e32 v36, s6, v112
	ds_write_b32 v36, v41
	v_add_u32_e32 v36, s7, v112
	ds_write_b32 v36, v45
	v_add_u32_e32 v36, s33, v113
	ds_write_b32 v36, v38
	v_add_u32_e32 v36, s6, v113
	ds_write_b32 v36, v42
	v_add_u32_e32 v36, s7, v113
	ds_write_b32 v36, v46
	v_add_u32_e32 v36, s33, v114
	ds_write_b32 v36, v39
	v_add_u32_e32 v36, s6, v114
	ds_write_b32 v36, v43
	v_add_u32_e32 v36, s7, v114
	ds_write_b32 v36, v47
	v_add_u32_e32 v36, s33, v115
	ds_write_b32 v36, v76
	v_add_u32_e32 v36, s6, v115
	ds_write_b32 v36, v80
	v_add_u32_e32 v36, s7, v115
	ds_write_b32 v36, v84
	v_add_u32_e32 v36, s33, v116
	ds_write_b32 v36, v77
	v_add_u32_e32 v36, s6, v116
	ds_write_b32 v36, v81
	v_add_u32_e32 v36, s7, v116
	ds_write_b32 v36, v85
	v_add_u32_e32 v36, s33, v117
	ds_write_b32 v36, v78
	v_add_u32_e32 v36, s6, v117
	ds_write_b32 v36, v82
	v_add_u32_e32 v36, s7, v117
	ds_write_b32 v36, v86
	v_add_u32_e32 v36, s33, v118
	ds_write_b32 v36, v79
	v_add_u32_e32 v36, s6, v118
	ds_write_b32 v36, v83
	v_add_u32_e32 v36, s7, v118
	ds_write_b32 v36, v87


; #define LAS __attribute__((address_space(3)))
; #define LBAR() asm volatile("s_waitcnt lgkmcnt(0)\n\ts_barrier" ::: "memory")
; #define TSUB(k) do { } while (0)
; __device__ __forceinline__ void rwkv_chunk_group(Frame& F, int bc, unsigned long long& tsub) {
;     ...
;         LBAR();
;     }
;     TSUB(1);
;     {
;         const int gc = h * 64 + ch;
;         const float mur = mu[gc], muk = mu[512 + gc], muv = mu[1024 + gc];
;         const float w0 = (PRM + 2048)[gc], a0 = (PRM + 2560)[gc], k_k = (PRM + 3072)[gc], k_a = (PRM + 3584)[gc], r_k = (PRM + 4096)[gc];
;         float rr[8], kp[8], vv[8], aa[8], bb[8], ld[8], vbv[8], ggv[8];
;         float pr = bf2f(raw[0][0]), pk = bf2f(raw[0][1]), pv = bf2f(raw[0][2]);
;         bf16* VBp = (bf16*)(F.ws + WS_VB) + (size_t)item * 4096; bf16* Gp = (bf16*)(F.ws + WS_G) + (size_t)item * 4096;
;         float run = 0.f; float kkv[8], icv[8], sq[8], bq[8];
; #pragma unroll
;         for (int tt = 0; tt < 8; ++tt) { const int t = tb + tt;
;             const float cr = bf2f(raw[tt + 1][0]), ck = bf2f(raw[tt + 1][1]), cv = bf2f(raw[tt + 1][2]);
;             const float r = cr + (pr - cr) * mur, k = ck + (pk - ck) * muk, v = cv + (pv - cv) * muv; pr = cr; pk = ck; pv = cv;
;             const float wl = *(const LAS float*)(L + L_WL + (t * 65 + ch) * 4), al = *(const LAS float*)(L + L_AL + (t * 65 + ch) * 4), gl = *(const LAS float*)(L + L_GL + (t * 65 + ch) * 4);
	s_waitcnt lgkmcnt(0)
	s_barrier
	v_add_u32_e32 v41, s7, v120
	v_add_u32_e32 v87, s7, v122

; __device__ __forceinline__ void rwkv_chunk_group(Frame& F, int bc, unsigned long long& tsub) {
;     ...
;         const float mur = mu[gc], muk = mu[512 + gc], muv = mu[1024 + gc];
;         const float w0 = (PRM + 2048)[gc], a0 = (PRM + 2560)[gc], k_k = (PRM + 3072)[gc], k_a = (PRM + 3584)[gc], r_k = (PRM + 4096)[gc];
	s_waitcnt vmcnt(0)
	v_mov_b32_e32 v95, v224
	v_mov_b32_e32 v42, v225


; __device__ __forceinline__ void rwkv_chunk_group(Frame& F, int bc, unsigned long long& tsub) {
;     ...
;         const float mur = mu[gc], muk = mu[512 + gc], muv = mu[1024 + gc];
;         const float w0 = (PRM + 2048)[gc], a0 = (PRM + 2560)[gc], k_k = (PRM + 3072)[gc], k_a = (PRM + 3584)[gc], r_k = (PRM + 4096)[gc];
	s_nop 0


; #define LAS __attribute__((address_space(3)))
; __device__ __forceinline__ void rwkv_chunk_group(Frame& F, int bc, unsigned long long& tsub) {
;     ...
;         for (int tt = 0; tt < 8; ++tt) { const int t = tb + tt;
;             const float cr = bf2f(raw[tt + 1][0]), ck = bf2f(raw[tt + 1][1]), cv = bf2f(raw[tt + 1][2]);
;             const float r = cr + (pr - cr) * mur, k = ck + (pk - ck) * muk, v = cv + (pv - cv) * muv; pr = cr; pk = ck; pv = cv;
;             const float wl = *(const LAS float*)(L + L_WL + (t * 65 + ch) * 4), al = *(const LAS float*)(L + L_AL + (t * 65 + ch) * 4), gl = *(const LAS float*)(L + L_GL + (t * 65 + ch) * 4);
	v_mov_b32_e32 v52, v226
	v_add_u32_e32 v83, s7, v121

; __device__ __forceinline__ void rwkv_chunk_group(Frame& F, int bc, unsigned long long& tsub) {
;     ...
;         const float mur = mu[gc], muk = mu[512 + gc], muv = mu[1024 + gc];
;         const float w0 = (PRM + 2048)[gc], a0 = (PRM + 2560)[gc], k_k = (PRM + 3072)[gc], k_a = (PRM + 3584)[gc], r_k = (PRM + 4096)[gc];
	v_mov_b32_e32 v45, v227


; __device__ __forceinline__ void rwkv_chunk_group(Frame& F, int bc, unsigned long long& tsub) {
;     ...
;         for (int tt = 0; tt < 8; ++tt) { const int t = tb + tt;
;             const float cr = bf2f(raw[tt + 1][0]), ck = bf2f(raw[tt + 1][1]), cv = bf2f(raw[tt + 1][2]);
;             const float r = cr + (pr - cr) * mur, k = ck + (pk - ck) * muk, v = cv + (pv - cv) * muv; pr = cr; pk = ck; pv = cv;
	v_lshlrev_b32_e32 v82, 16, v155
	v_and_b32_e32 v77, 0xffff0000, v167

; __device__ __forceinline__ void rwkv_chunk_group(Frame& F, int bc, unsigned long long& tsub) {
;     ...
;         const float mur = mu[gc], muk = mu[512 + gc], muv = mu[1024 + gc];
;         const float w0 = (PRM + 2048)[gc], a0 = (PRM + 2560)[gc], k_k = (PRM + 3072)[gc], k_a = (PRM + 3584)[gc], r_k = (PRM + 4096)[gc];
	v_mov_b32_e32 v43, v228


; __device__ __forceinline__ void rwkv_chunk_group(Frame& F, int bc, unsigned long long& tsub) {
;     ...
;         for (int tt = 0; tt < 8; ++tt) { const int t = tb + tt;
;             const float cr = bf2f(raw[tt + 1][0]), ck = bf2f(raw[tt + 1][1]), cv = bf2f(raw[tt + 1][2]);
;             const float r = cr + (pr - cr) * mur, k = ck + (pk - ck) * muk, v = cv + (pv - cv) * muv; pr = cr; pk = ck; pv = cv;
	v_lshlrev_b32_e32 v76, 16, v167
	v_and_b32_e32 v79, 0xffff0000, v166


; __device__ __forceinline__ void rwkv_chunk_group(Frame& F, int bc, unsigned long long& tsub) {
;     ...
;         const float mur = mu[gc], muk = mu[512 + gc], muv = mu[1024 + gc];
;         const float w0 = (PRM + 2048)[gc], a0 = (PRM + 2560)[gc], k_k = (PRM + 3072)[gc], k_a = (PRM + 3584)[gc], r_k = (PRM + 4096)[gc];
;         float rr[8], kp[8], vv[8], aa[8], bb[8], ld[8], vbv[8], ggv[8];
;         float pr = bf2f(raw[0][0]), pk = bf2f(raw[0][1]), pv = bf2f(raw[0][2]);
;         bf16* VBp = (bf16*)(F.ws + WS_VB) + (size_t)item * 4096; bf16* Gp = (bf16*)(F.ws + WS_G) + (size_t)item * 4096;
;         float run = 0.f; float kkv[8], icv[8], sq[8], bq[8];
; #pragma unroll
;         for (int tt = 0; tt < 8; ++tt) { const int t = tb + tt;
;             const float cr = bf2f(raw[tt + 1][0]), ck = bf2f(raw[tt + 1][1]), cv = bf2f(raw[tt + 1][2]);
;             const float r = cr + (pr - cr) * mur, k = ck + (pk - ck) * muk, v = cv + (pv - cv) * muv; pr = cr; pk = ck; pv = cv;
	v_mov_b32_e32 v44, v229
	v_lshlrev_b32_e32 v78, 16, v166

; __device__ __forceinline__ void rwkv_chunk_group(Frame& F, int bc, unsigned long long& tsub) {
;     ...
;         const float mur = mu[gc], muk = mu[512 + gc], muv = mu[1024 + gc];
;         const float w0 = (PRM + 2048)[gc], a0 = (PRM + 2560)[gc], k_k = (PRM + 3072)[gc], k_a = (PRM + 3584)[gc], r_k = (PRM + 4096)[gc];
	v_mov_b32_e32 v46, v230


; __device__ __forceinline__ void rwkv_chunk_group(Frame& F, int bc, unsigned long long& tsub) {
;     ...
;         for (int tt = 0; tt < 8; ++tt) { const int t = tb + tt;
;             const float cr = bf2f(raw[tt + 1][0]), ck = bf2f(raw[tt + 1][1]), cv = bf2f(raw[tt + 1][2]);
;             const float r = cr + (pr - cr) * mur, k = ck + (pk - ck) * muk, v = cv + (pv - cv) * muv; pr = cr; pk = ck; pv = cv;
	v_lshlrev_b32_e32 v86, 16, v157
	v_and_b32_e32 v91, 0xffff0000, v168

; #define LAS __attribute__((address_space(3)))
; __device__ __forceinline__ float sigmoidf_(float x) { return __builtin_amdgcn_rcpf(1.0f + __expf(-x)); }
; __device__ __forceinline__ void rwkv_chunk_group(Frame& F, int bc, unsigned long long& tsub) {
;     ...
;         for (int tt = 0; tt < 8; ++tt) { const int t = tb + tt;
;             const float cr = bf2f(raw[tt + 1][0]), ck = bf2f(raw[tt + 1][1]), cv = bf2f(raw[tt + 1][2]);
;             const float r = cr + (pr - cr) * mur, k = ck + (pk - ck) * muk, v = cv + (pv - cv) * muv; pr = cr; pk = ck; pv = cv;
;             const float wl = *(const LAS float*)(L + L_WL + (t * 65 + ch) * 4), al = *(const LAS float*)(L + L_AL + (t * 65 + ch) * 4), gl = *(const LAS float*)(L + L_GL + (t * 65 + ch) * 4);
;             const float z = -(w0 + wl); const float sp = fmaxf(z, 0.f) + __logf(1.f + __expf(-fabsf(z)));
;             const float lgd = -__expf(-sp - 0.5f);
;             const float ic = sigmoidf_(a0 + al);
	v_mov_b32_e32 v103, v231
	v_lshlrev_b32_e32 v36, 16, v153
	v_lshlrev_b32_e32 v37, 16, v154
	v_sub_f32_e32 v36, v36, v37
	v_add_u32_e32 v38, s6, v119
	v_add_u32_e32 v39, s7, v119
	ds_read_b32 v38, v38
	ds_read_b32 v47, v39
	ds_read_b32 v177, v41
	ds_read_b32 v185, v87
	ds_read_b32 v191, v191
	v_lshlrev_b32_e32 v90, 16, v168
	v_and_b32_e32 v85, 0xffff0000, v169
	ds_read_b32 v182, v83
	ds_read_b32 v96, v96
	ds_read_b32 v189, v93
	ds_read_b32 v193, v97
	ds_read_b32 v194, v192
	s_waitcnt vmcnt(7)
	v_fma_f32 v173, v36, v95, v37
	v_add_u32_e32 v36, s33, v119
	ds_read_b32 v36, v36
	s_waitcnt vmcnt(4) lgkmcnt(0)
	v_add_f32_e32 v36, v45, v36
	v_max_f32_e64 v39, -v36, 0
	v_mul_f32_e64 v36, |v36|, s1
	v_exp_f32_e32 v36, v36
	s_nop 0
	v_add_f32_e32 v36, 1.0, v36

; __device__ __forceinline__ void rwkv_chunk_group(Frame& F, int bc, unsigned long long& tsub) {
;     ...
;             const float z = -(w0 + wl); const float sp = fmaxf(z, 0.f) + __logf(1.f + __expf(-fabsf(z)));
	s_nop 1


; __device__ __forceinline__ void rwkv_chunk_group(Frame& F, int bc, unsigned long long& tsub) {
;     ...
;             const float z = -(w0 + wl); const float sp = fmaxf(z, 0.f) + __logf(1.f + __expf(-fabsf(z)));
	v_log_f32_e32 v36, v36
	s_nop 0
	v_mul_f32_e32 v40, 0x3f317217, v36
	v_fma_f32 v40, v36, s9, -v40
	v_fmac_f32_e32 v40, 0x3377d1cf, v36
	v_fmac_f32_e32 v40, 0x3f317217, v36

; __device__ __forceinline__ void rwkv_chunk_group(Frame& F, int bc, unsigned long long& tsub) {
;     ...
;             const float z = -(w0 + wl); const float sp = fmaxf(z, 0.f) + __logf(1.f + __expf(-fabsf(z)));
	s_nop 1
	v_mov_b32_e32 v36, v40


; #define LAS __attribute__((address_space(3)))
; __device__ __forceinline__ float sigmoidf_(float x) { return __builtin_amdgcn_rcpf(1.0f + __expf(-x)); }
; __device__ __forceinline__ void rwkv_chunk_group(Frame& F, int bc, unsigned long long& tsub) {
;     ...
;         for (int tt = 0; tt < 8; ++tt) { const int t = tb + tt;
;             const float cr = bf2f(raw[tt + 1][0]), ck = bf2f(raw[tt + 1][1]), cv = bf2f(raw[tt + 1][2]);
;             const float r = cr + (pr - cr) * mur, k = ck + (pk - ck) * muk, v = cv + (pv - cv) * muv; pr = cr; pk = ck; pv = cv;
;             const float wl = *(const LAS float*)(L + L_WL + (t * 65 + ch) * 4), al = *(const LAS float*)(L + L_AL + (t * 65 + ch) * 4), gl = *(const LAS float*)(L + L_GL + (t * 65 + ch) * 4);
;             const float z = -(w0 + wl); const float sp = fmaxf(z, 0.f) + __logf(1.f + __expf(-fabsf(z)));
;             const float lgd = -__expf(-sp - 0.5f);
;             const float ic = sigmoidf_(a0 + al);
	v_add_f32_e32 v36, v39, v36
	v_add_u32_e32 v39, s33, v120
	ds_read_b32 v39, v39
	v_sub_f32_e32 v36, -0.5, v36
	v_mul_f32_e32 v36, 0x3fb8aa3b, v36
	v_exp_f32_e32 v102, v36
	s_waitcnt vmcnt(3)
	v_add_f32_e32 v36, v43, v38
	v_mul_f32_e32 v36, 0xbfb8aa3b, v36
	v_add_u32_e32 v40, s6, v120
	v_exp_f32_e32 v36, v36
	ds_read_b32 v40, v40
	s_waitcnt lgkmcnt(1)
	v_add_f32_e32 v39, v45, v39
	v_max_f32_e64 v41, -v39, 0
	v_mul_f32_e64 v39, |v39|, s1
	v_exp_f32_e32 v39, v39
	v_add_f32_e32 v36, 1.0, v36
	v_rcp_f32_e32 v38, v36
	v_sub_f32_e32 v36, v37, v82
	v_fma_f32 v174, v36, v95, v82
	v_and_b32_e32 v37, 0xffff0000, v161
	v_lshlrev_b32_e32 v36, 16, v161
	v_add_f32_e32 v39, 1.0, v39
	v_add_f32_e64 v36, v36, -v76
	v_add_f32_e64 v37, v37, -v77

; __device__ __forceinline__ void rwkv_chunk_group(Frame& F, int bc, unsigned long long& tsub) {
;     ...
;             const float r = cr + (pr - cr) * mur, k = ck + (pk - ck) * muk, v = cv + (pv - cv) * muv; pr = cr; pk = ck; pv = cv;
	v_fma_f32 v36, v36, v52, v76
	v_fma_f32 v37, v37, v52, v77
	s_nop 0


; __device__ __forceinline__ void rwkv_chunk_group(Frame& F, int bc, unsigned long long& tsub) {
;     ...
;             const float z = -(w0 + wl); const float sp = fmaxf(z, 0.f) + __logf(1.f + __expf(-fabsf(z)));
	v_log_f32_e32 v39, v39
	s_nop 0
	v_mul_f32_e32 v76, 0x3f317217, v39
	v_fma_f32 v76, v39, s9, -v76
	v_fmac_f32_e32 v76, 0x3377d1cf, v39
	v_fmac_f32_e32 v76, 0x3f317217, v39

; __device__ __forceinline__ void rwkv_chunk_group(Frame& F, int bc, unsigned long long& tsub) {
;     ...
;             const float z = -(w0 + wl); const float sp = fmaxf(z, 0.f) + __logf(1.f + __expf(-fabsf(z)));
	s_nop 1
	v_mov_b32_e32 v39, v76


; #define LAS __attribute__((address_space(3)))
; __device__ __forceinline__ float sigmoidf_(float x) { return __builtin_amdgcn_rcpf(1.0f + __expf(-x)); }
; __device__ __forceinline__ void rwkv_chunk_group(Frame& F, int bc, unsigned long long& tsub) {
;     ...
;             const float r = cr + (pr - cr) * mur, k = ck + (pk - ck) * muk, v = cv + (pv - cv) * muv; pr = cr; pk = ck; pv = cv;
;             const float wl = *(const LAS float*)(L + L_WL + (t * 65 + ch) * 4), al = *(const LAS float*)(L + L_AL + (t * 65 + ch) * 4), gl = *(const LAS float*)(L + L_GL + (t * 65 + ch) * 4);
;             const float z = -(w0 + wl); const float sp = fmaxf(z, 0.f) + __logf(1.f + __expf(-fabsf(z)));
;             const float lgd = -__expf(-sp - 0.5f);
;             const float ic = sigmoidf_(a0 + al);
;             const float kv = k * k_k; const float kq = k * (1.f + (ic - 1.f) * k_a);
;             kkv[tt] = kv; icv[tt] = ic; sq[tt] = kv * kv; bq[tt] = r * kq * r_k;
	v_add_f32_e32 v39, v41, v39
	v_sub_f32_e32 v39, -0.5, v39
	v_mul_f32_e32 v39, 0x3fb8aa3b, v39
	v_exp_f32_e32 v76, v39
	s_waitcnt lgkmcnt(0)
	v_add_f32_e32 v39, v43, v40
	v_mul_f32_e32 v39, 0xbfb8aa3b, v39
	v_exp_f32_e32 v39, v39
	v_and_b32_e32 v41, 0xffff0000, v160
	v_lshlrev_b32_e32 v40, 16, v160
	v_add_f32_e64 v40, v40, -v78
	v_add_f32_e64 v41, v41, -v79
	v_add_f32_e32 v39, 1.0, v39
	v_rcp_f32_e32 v39, v39
	v_fma_f32 v80, v40, v42, v78
	v_fma_f32 v81, v41, v42, v79
	v_sub_f32_e64 v176, -v102, v76
	v_lshlrev_b32_e32 v76, 16, v156
	v_add_f32_e64 v40, v38, -1.0
	v_add_f32_e64 v41, v39, -1.0
	s_waitcnt vmcnt(1)
	v_fma_f32 v40, v46, v40, 1.0
	v_fma_f32 v41, v46, v41, 1.0
	v_mul_f32_e32 v40, v80, v40
	v_mul_f32_e32 v41, v81, v41
	s_nop 0
	v_mul_f32_e32 v78, v173, v40
	s_waitcnt vmcnt(0)
	v_mul_f32_e32 v101, v103, v78
	v_mul_f32_e32 v78, v174, v41
	v_mul_f32_e32 v100, v103, v78
	v_sub_f32_e32 v78, v82, v76
	v_fma_f32 v175, v78, v95, v76
	v_add_u32_e32 v78, s33, v121
	ds_read_b32 v78, v78
	v_add_u32_e32 v82, s6, v121
	ds_read_b32 v82, v82
	v_sub_f32_e32 v76, v76, v86
	v_fma_f32 v178, v76, v95, v86
	s_waitcnt lgkmcnt(1)
	v_add_f32_e32 v78, v45, v78
	v_max_f32_e64 v83, -v78, 0
	v_mul_f32_e64 v78, |v78|, s1
	v_exp_f32_e32 v78, v78
	s_waitcnt lgkmcnt(0)
	v_add_f32_e32 v82, v43, v82
	v_mul_f32_e32 v82, 0xbfb8aa3b, v82
	v_exp_f32_e32 v82, v82
	v_add_f32_e32 v78, 1.0, v78

; __device__ __forceinline__ float sigmoidf_(float x) { return __builtin_amdgcn_rcpf(1.0f + __expf(-x)); }
; __device__ __forceinline__ void rwkv_chunk_group(Frame& F, int bc, unsigned long long& tsub) {
;     ...
;             const float ic = sigmoidf_(a0 + al);
	v_add_f32_e32 v82, 1.0, v82
	s_nop 0


; __device__ __forceinline__ float sigmoidf_(float x) { return __builtin_amdgcn_rcpf(1.0f + __expf(-x)); }
; __device__ __forceinline__ void rwkv_chunk_group(Frame& F, int bc, unsigned long long& tsub) {
;     ...
;             const float z = -(w0 + wl); const float sp = fmaxf(z, 0.f) + __logf(1.f + __expf(-fabsf(z)));
;             const float lgd = -__expf(-sp - 0.5f);
;             const float ic = sigmoidf_(a0 + al);
	v_log_f32_e32 v78, v78
	v_rcp_f32_e32 v82, v82
	v_mul_f32_e32 v84, 0x3f317217, v78
	v_fma_f32 v84, v78, s9, -v84
	v_fmac_f32_e32 v84, 0x3377d1cf, v78
	v_fmac_f32_e32 v84, 0x3f317217, v78

; __device__ __forceinline__ void rwkv_chunk_group(Frame& F, int bc, unsigned long long& tsub) {
;     ...
;             const float z = -(w0 + wl); const float sp = fmaxf(z, 0.f) + __logf(1.f + __expf(-fabsf(z)));
	s_nop 1
	v_mov_b32_e32 v78, v84


; #define LAS __attribute__((address_space(3)))
; __device__ __forceinline__ float sigmoidf_(float x) { return __builtin_amdgcn_rcpf(1.0f + __expf(-x)); }
; __device__ __forceinline__ void rwkv_chunk_group(Frame& F, int bc, unsigned long long& tsub) {
;     ...
;         for (int tt = 0; tt < 8; ++tt) { const int t = tb + tt;
;             const float cr = bf2f(raw[tt + 1][0]), ck = bf2f(raw[tt + 1][1]), cv = bf2f(raw[tt + 1][2]);
;             const float r = cr + (pr - cr) * mur, k = ck + (pk - ck) * muk, v = cv + (pv - cv) * muv; pr = cr; pk = ck; pv = cv;
;             const float wl = *(const LAS float*)(L + L_WL + (t * 65 + ch) * 4), al = *(const LAS float*)(L + L_AL + (t * 65 + ch) * 4), gl = *(const LAS float*)(L + L_GL + (t * 65 + ch) * 4);
;             const float z = -(w0 + wl); const float sp = fmaxf(z, 0.f) + __logf(1.f + __expf(-fabsf(z)));
;             const float lgd = -__expf(-sp - 0.5f);
;             const float ic = sigmoidf_(a0 + al);
	v_add_f32_e32 v78, v83, v78
	v_sub_f32_e32 v78, -0.5, v78
	v_mul_f32_e32 v78, 0x3fb8aa3b, v78
	v_exp_f32_e32 v78, v78
	v_add_u32_e32 v83, s6, v122
	ds_read_b32 v83, v83
	v_lshlrev_b32_e32 v84, 16, v169
	v_sub_f32_e32 v179, v176, v78
	v_add_u32_e32 v78, s33, v122
	ds_read_b32 v78, v78
	v_pk_mov_b32 v[76:77], v[76:77], v[84:85] op_sel:[1,0]
	s_waitcnt lgkmcnt(0)
	v_add_f32_e32 v78, v45, v78
	v_max_f32_e64 v87, -v78, 0
	v_mul_f32_e64 v78, |v78|, s1
	v_exp_f32_e32 v78, v78
	v_add_f32_e64 v76, v76, -v84
	v_add_f32_e64 v77, v77, -v85
	v_add_f32_e32 v78, 1.0, v78

; __device__ __forceinline__ void rwkv_chunk_group(Frame& F, int bc, unsigned long long& tsub) {
;     ...
;             const float r = cr + (pr - cr) * mur, k = ck + (pk - ck) * muk, v = cv + (pv - cv) * muv; pr = cr; pk = ck; pv = cv;
	v_fma_f32 v76, v76, v52, v84
	v_fma_f32 v77, v77, v52, v85
	s_nop 0


; __device__ __forceinline__ void rwkv_chunk_group(Frame& F, int bc, unsigned long long& tsub) {
;     ...
;             const float z = -(w0 + wl); const float sp = fmaxf(z, 0.f) + __logf(1.f + __expf(-fabsf(z)));
	v_log_f32_e32 v78, v78
	s_nop 0
	v_mul_f32_e32 v88, 0x3f317217, v78
	v_fma_f32 v88, v78, s9, -v88
	v_fmac_f32_e32 v88, 0x3377d1cf, v78
	v_fmac_f32_e32 v88, 0x3f317217, v78

; __device__ __forceinline__ void rwkv_chunk_group(Frame& F, int bc, unsigned long long& tsub) {
;     ...
;             const float z = -(w0 + wl); const float sp = fmaxf(z, 0.f) + __logf(1.f + __expf(-fabsf(z)));
	s_nop 1
	v_mov_b32_e32 v78, v88


; #define LAS __attribute__((address_space(3)))
; __device__ __forceinline__ float sigmoidf_(float x) { return __builtin_amdgcn_rcpf(1.0f + __expf(-x)); }
; __device__ __forceinline__ void rwkv_chunk_group(Frame& F, int bc, unsigned long long& tsub) {
;     ...
;         for (int tt = 0; tt < 8; ++tt) { const int t = tb + tt;
;             const float cr = bf2f(raw[tt + 1][0]), ck = bf2f(raw[tt + 1][1]), cv = bf2f(raw[tt + 1][2]);
;             const float r = cr + (pr - cr) * mur, k = ck + (pk - ck) * muk, v = cv + (pv - cv) * muv; pr = cr; pk = ck; pv = cv;
;             const float wl = *(const LAS float*)(L + L_WL + (t * 65 + ch) * 4), al = *(const LAS float*)(L + L_AL + (t * 65 + ch) * 4), gl = *(const LAS float*)(L + L_GL + (t * 65 + ch) * 4);
;             const float z = -(w0 + wl); const float sp = fmaxf(z, 0.f) + __logf(1.f + __expf(-fabsf(z)));
;             const float lgd = -__expf(-sp - 0.5f);
;             const float ic = sigmoidf_(a0 + al);
;             const float kv = k * k_k; const float kq = k * (1.f + (ic - 1.f) * k_a);
;             kkv[tt] = kv; icv[tt] = ic; sq[tt] = kv * kv; bq[tt] = r * kq * r_k;
	v_add_f32_e32 v78, v87, v78
	v_sub_f32_e32 v78, -0.5, v78
	v_mul_f32_e32 v78, 0x3fb8aa3b, v78
	v_exp_f32_e32 v87, v78
	v_add_f32_e32 v78, v43, v83
	v_mul_f32_e32 v78, 0xbfb8aa3b, v78
	v_exp_f32_e32 v78, v78
	v_sub_f32_e32 v181, v179, v87
	v_lshlrev_b32_e32 v87, 16, v158
	v_sub_f32_e32 v86, v86, v87
	v_add_f32_e32 v78, 1.0, v78
	v_rcp_f32_e32 v83, v78
	v_pk_mov_b32 v[78:79], v[78:79], v[90:91] op_sel:[1,0]
	v_fma_f32 v180, v86, v95, v87
	v_add_f32_e64 v78, v78, -v90
	v_add_f32_e64 v79, v79, -v91
	v_add_u32_e32 v86, s33, v123
	v_fma_f32 v88, v78, v42, v90
	v_fma_f32 v89, v79, v42, v91
	v_add_f32_e64 v78, v82, -1.0
	v_add_f32_e64 v79, v83, -1.0
	ds_read_b32 v86, v86
	v_fma_f32 v78, v46, v78, 1.0
	v_fma_f32 v79, v46, v79, 1.0
	v_mul_f32_e32 v78, v88, v78
	v_mul_f32_e32 v79, v89, v79
	s_nop 0
	v_mul_f32_e32 v92, v175, v78
	v_mul_f32_e32 v187, v103, v92
	v_mul_f32_e32 v92, v178, v79
	v_mul_f32_e32 v186, v103, v92
	v_add_u32_e32 v92, s6, v123
	ds_read_b32 v92, v92
	s_waitcnt lgkmcnt(1)
	v_add_f32_e32 v86, v45, v86
	v_max_f32_e64 v93, -v86, 0
	v_mul_f32_e64 v86, |v86|, s1
	v_exp_f32_e32 v86, v86
	s_nop 0
	v_add_f32_e32 v86, 1.0, v86

; __device__ __forceinline__ void rwkv_chunk_group(Frame& F, int bc, unsigned long long& tsub) {
;     ...
;             const float z = -(w0 + wl); const float sp = fmaxf(z, 0.f) + __logf(1.f + __expf(-fabsf(z)));
	s_nop 1


; __device__ __forceinline__ void rwkv_chunk_group(Frame& F, int bc, unsigned long long& tsub) {
;     ...
;             const float z = -(w0 + wl); const float sp = fmaxf(z, 0.f) + __logf(1.f + __expf(-fabsf(z)));
	v_log_f32_e32 v86, v86
	s_nop 0
	v_mul_f32_e32 v94, 0x3f317217, v86
	v_fma_f32 v94, v86, s9, -v94
	v_fmac_f32_e32 v94, 0x3377d1cf, v86
	v_fmac_f32_e32 v94, 0x3f317217, v86

; __device__ __forceinline__ void rwkv_chunk_group(Frame& F, int bc, unsigned long long& tsub) {
;     ...
;             const float z = -(w0 + wl); const float sp = fmaxf(z, 0.f) + __logf(1.f + __expf(-fabsf(z)));
	s_nop 1
	v_mov_b32_e32 v86, v94


; #define LAS __attribute__((address_space(3)))
; __device__ __forceinline__ float sigmoidf_(float x) { return __builtin_amdgcn_rcpf(1.0f + __expf(-x)); }
; __device__ __forceinline__ void rwkv_chunk_group(Frame& F, int bc, unsigned long long& tsub) {
;     ...
;         for (int tt = 0; tt < 8; ++tt) { const int t = tb + tt;
;             const float cr = bf2f(raw[tt + 1][0]), ck = bf2f(raw[tt + 1][1]), cv = bf2f(raw[tt + 1][2]);
;             const float r = cr + (pr - cr) * mur, k = ck + (pk - ck) * muk, v = cv + (pv - cv) * muv; pr = cr; pk = ck; pv = cv;
;             const float wl = *(const LAS float*)(L + L_WL + (t * 65 + ch) * 4), al = *(const LAS float*)(L + L_AL + (t * 65 + ch) * 4), gl = *(const LAS float*)(L + L_GL + (t * 65 + ch) * 4);
;             const float z = -(w0 + wl); const float sp = fmaxf(z, 0.f) + __logf(1.f + __expf(-fabsf(z)));
;             const float lgd = -__expf(-sp - 0.5f);
;             const float ic = sigmoidf_(a0 + al);
	v_lshlrev_b32_e32 v94, 16, v159
	v_sub_f32_e32 v87, v87, v94
	v_fma_f32 v183, v87, v95, v94
	v_add_u32_e32 v87, s33, v124
	ds_read_b32 v87, v87
	v_add_f32_e32 v86, v93, v86
	v_sub_f32_e32 v86, -0.5, v86
	v_mul_f32_e32 v86, 0x3fb8aa3b, v86
	v_exp_f32_e32 v93, v86
	s_waitcnt lgkmcnt(0)
	v_add_f32_e32 v87, v45, v87
	v_max_f32_e64 v97, -v87, 0
	v_mul_f32_e64 v87, |v87|, s1
	v_exp_f32_e32 v87, v87
	v_add_f32_e32 v86, v43, v92
	v_mul_f32_e32 v86, 0xbfb8aa3b, v86
	v_exp_f32_e32 v86, v86
	v_add_f32_e32 v87, 1.0, v87

; __device__ __forceinline__ float sigmoidf_(float x) { return __builtin_amdgcn_rcpf(1.0f + __expf(-x)); }
; __device__ __forceinline__ void rwkv_chunk_group(Frame& F, int bc, unsigned long long& tsub) {
;     ...
;             const float lgd = -__expf(-sp - 0.5f);
;             const float ic = sigmoidf_(a0 + al);
;             const float kv = k * k_k; const float kq = k * (1.f + (ic - 1.f) * k_a);
;             kkv[tt] = kv; icv[tt] = ic; sq[tt] = kv * kv; bq[tt] = r * kq * r_k;
;             rr[tt] = r; kp[tt] = kq; vv[tt] = v; run += lgd; ld[tt] = run; ggv[tt] = gl;
	v_sub_f32_e32 v184, v181, v93
	v_add_f32_e32 v86, 1.0, v86


; #define LAS __attribute__((address_space(3)))
; __device__ __forceinline__ float sigmoidf_(float x) { return __builtin_amdgcn_rcpf(1.0f + __expf(-x)); }
; __device__ __forceinline__ void rwkv_chunk_group(Frame& F, int bc, unsigned long long& tsub) {
;     ...
;             const float cr = bf2f(raw[tt + 1][0]), ck = bf2f(raw[tt + 1][1]), cv = bf2f(raw[tt + 1][2]);
;             const float r = cr + (pr - cr) * mur, k = ck + (pk - ck) * muk, v = cv + (pv - cv) * muv; pr = cr; pk = ck; pv = cv;
;             const float wl = *(const LAS float*)(L + L_WL + (t * 65 + ch) * 4), al = *(const LAS float*)(L + L_AL + (t * 65 + ch) * 4), gl = *(const LAS float*)(L + L_GL + (t * 65 + ch) * 4);
;             const float z = -(w0 + wl); const float sp = fmaxf(z, 0.f) + __logf(1.f + __expf(-fabsf(z)));
;             const float lgd = -__expf(-sp - 0.5f);
;             const float ic = sigmoidf_(a0 + al);
	v_log_f32_e32 v87, v87
	v_rcp_f32_e32 v86, v86
	v_sub_f32_e32 v94, v94, v197
	v_and_b32_e32 v93, 0xffff0000, v171
	v_mul_f32_e32 v98, 0x3f317217, v87
	v_fma_f32 v98, v87, s9, -v98
	v_fmac_f32_e32 v98, 0x3377d1cf, v87
	v_fmac_f32_e32 v98, 0x3f317217, v87

; #define LAS __attribute__((address_space(3)))
; __device__ __forceinline__ void rwkv_chunk_group(Frame& F, int bc, unsigned long long& tsub) {
;     ...
;         for (int tt = 0; tt < 8; ++tt) { const int t = tb + tt;
;             const float cr = bf2f(raw[tt + 1][0]), ck = bf2f(raw[tt + 1][1]), cv = bf2f(raw[tt + 1][2]);
;             const float r = cr + (pr - cr) * mur, k = ck + (pk - ck) * muk, v = cv + (pv - cv) * muv; pr = cr; pk = ck; pv = cv;
;             const float wl = *(const LAS float*)(L + L_WL + (t * 65 + ch) * 4), al = *(const LAS float*)(L + L_AL + (t * 65 + ch) * 4), gl = *(const LAS float*)(L + L_GL + (t * 65 + ch) * 4);
;             const float z = -(w0 + wl); const float sp = fmaxf(z, 0.f) + __logf(1.f + __expf(-fabsf(z)));
	v_lshlrev_b32_e32 v92, 16, v171
	v_pk_mov_b32 v[84:85], v[84:85], v[92:93] op_sel:[1,0]
	v_mov_b32_e32 v87, v98


; #define LAS __attribute__((address_space(3)))
; __device__ __forceinline__ float sigmoidf_(float x) { return __builtin_amdgcn_rcpf(1.0f + __expf(-x)); }
; __device__ __forceinline__ void rwkv_chunk_group(Frame& F, int bc, unsigned long long& tsub) {
;     ...
;         for (int tt = 0; tt < 8; ++tt) { const int t = tb + tt;
;             const float cr = bf2f(raw[tt + 1][0]), ck = bf2f(raw[tt + 1][1]), cv = bf2f(raw[tt + 1][2]);
;             const float r = cr + (pr - cr) * mur, k = ck + (pk - ck) * muk, v = cv + (pv - cv) * muv; pr = cr; pk = ck; pv = cv;
;             const float wl = *(const LAS float*)(L + L_WL + (t * 65 + ch) * 4), al = *(const LAS float*)(L + L_AL + (t * 65 + ch) * 4), gl = *(const LAS float*)(L + L_GL + (t * 65 + ch) * 4);
;             const float z = -(w0 + wl); const float sp = fmaxf(z, 0.f) + __logf(1.f + __expf(-fabsf(z)));
;             const float lgd = -__expf(-sp - 0.5f);
;             const float ic = sigmoidf_(a0 + al);
;             const float kv = k * k_k; const float kq = k * (1.f + (ic - 1.f) * k_a);
;             kkv[tt] = kv; icv[tt] = ic; sq[tt] = kv * kv; bq[tt] = r * kq * r_k;
;             rr[tt] = r; kp[tt] = kq; vv[tt] = v; run += lgd; ld[tt] = run; ggv[tt] = gl;
;         }
;         wave_sum8(sq); wave_sum8(bq);
	v_add_f32_e32 v87, v97, v87
	v_sub_f32_e32 v87, -0.5, v87
	v_mul_f32_e32 v87, 0x3fb8aa3b, v87
	v_exp_f32_e32 v188, v87
	v_add_f32_e32 v87, v43, v96
	v_mul_f32_e32 v87, 0xbfb8aa3b, v87
	v_exp_f32_e32 v87, v87
	v_and_b32_e32 v97, 0xffff0000, v170
	v_lshlrev_b32_e32 v96, 16, v170
	v_pk_mov_b32 v[90:91], v[90:91], v[96:97] op_sel:[1,0]
	v_add_f32_e32 v87, 1.0, v87
	v_rcp_f32_e32 v87, v87
	v_add_f32_e64 v90, v90, -v96
	v_add_f32_e64 v91, v91, -v97
	v_add_f32_e64 v84, v84, -v92
	v_add_f32_e64 v85, v85, -v93
	v_fma_f32 v98, v90, v42, v96
	v_fma_f32 v99, v91, v42, v97
	v_add_f32_e64 v90, v86, -1.0
	v_add_f32_e64 v91, v87, -1.0
	v_fma_f32 v84, v84, v52, v92
	v_fma_f32 v85, v85, v52, v93
	v_fma_f32 v90, v46, v90, 1.0
	v_fma_f32 v91, v46, v91, 1.0
	v_mul_f32_e32 v90, v98, v90
	v_mul_f32_e32 v91, v99, v91
	s_nop 0
	v_mul_f32_e32 v190, v180, v90
	v_mul_f32_e32 v196, v103, v190
	v_mul_f32_e32 v190, v183, v91
	v_mul_f32_e32 v195, v103, v190
	v_sub_f32_e32 v190, v184, v188
	v_fma_f32 v188, v94, v95, v197
	v_add_u32_e32 v94, s33, v125
	ds_read_b32 v94, v94
	v_permlane32_swap_b32_e32 v101, v196
	v_permlane32_swap_b32_e32 v100, v195
	s_waitcnt lgkmcnt(0)
	v_add_f32_e32 v94, v45, v94
	v_max_f32_e64 v192, -v94, 0
	v_mul_f32_e64 v94, |v94|, s1
	v_exp_f32_e32 v94, v94
	v_add_f32_e32 v201, v101, v196
	v_add_f32_e32 v195, v100, v195
	v_add_f32_e32 v94, 1.0, v94

; __device__ __forceinline__ void rwkv_chunk_group(Frame& F, int bc, unsigned long long& tsub) {
;     ...
;             const float z = -(w0 + wl); const float sp = fmaxf(z, 0.f) + __logf(1.f + __expf(-fabsf(z)));
	s_nop 1


; __device__ __forceinline__ void rwkv_chunk_group(Frame& F, int bc, unsigned long long& tsub) {
;     ...
;             const float z = -(w0 + wl); const float sp = fmaxf(z, 0.f) + __logf(1.f + __expf(-fabsf(z)));
	v_log_f32_e32 v94, v94
	s_nop 0
	v_mul_f32_e32 v198, 0x3f317217, v94
	v_fma_f32 v198, v94, s9, -v198
	v_fmac_f32_e32 v198, 0x3377d1cf, v94
	v_fmac_f32_e32 v198, 0x3f317217, v94

; __device__ __forceinline__ void rwkv_chunk_group(Frame& F, int bc, unsigned long long& tsub) {
;     ...
;             const float z = -(w0 + wl); const float sp = fmaxf(z, 0.f) + __logf(1.f + __expf(-fabsf(z)));
	s_nop 1
	v_mov_b32_e32 v94, v198


; #define LAS __attribute__((address_space(3)))
; __device__ __forceinline__ float sigmoidf_(float x) { return __builtin_amdgcn_rcpf(1.0f + __expf(-x)); }
; __device__ __forceinline__ void rwkv_chunk_group(Frame& F, int bc, unsigned long long& tsub) {
;     ...
;         for (int tt = 0; tt < 8; ++tt) { const int t = tb + tt;
;             const float cr = bf2f(raw[tt + 1][0]), ck = bf2f(raw[tt + 1][1]), cv = bf2f(raw[tt + 1][2]);
;             const float r = cr + (pr - cr) * mur, k = ck + (pk - ck) * muk, v = cv + (pv - cv) * muv; pr = cr; pk = ck; pv = cv;
;             const float wl = *(const LAS float*)(L + L_WL + (t * 65 + ch) * 4), al = *(const LAS float*)(L + L_AL + (t * 65 + ch) * 4), gl = *(const LAS float*)(L + L_GL + (t * 65 + ch) * 4);
;             const float z = -(w0 + wl); const float sp = fmaxf(z, 0.f) + __logf(1.f + __expf(-fabsf(z)));
;             const float lgd = -__expf(-sp - 0.5f);
;             const float ic = sigmoidf_(a0 + al);
	v_lshlrev_b32_e32 v198, 16, v172
	v_pk_mov_b32 v[92:93], v[92:93], v[198:199] op_sel:[1,0]
	v_add_f32_e32 v94, v192, v94
	v_add_f32_e64 v92, v92, -v198
	v_add_f32_e64 v93, v93, -v199
	v_sub_f32_e32 v94, -0.5, v94
	v_fma_f32 v92, v92, v52, v198
	v_fma_f32 v93, v93, v52, v199
	v_add_u32_e32 v52, s33, v126
	ds_read_b32 v52, v52
	v_mul_f32_e32 v94, 0x3fb8aa3b, v94
	v_exp_f32_e32 v192, v94
	v_add_f32_e32 v94, v43, v191
	v_lshlrev_b32_e32 v191, 16, v163
	v_sub_f32_e32 v197, v197, v191
	v_fmac_f32_e32 v191, v197, v95
	v_add_u32_e32 v95, s6, v126
	v_add_u32_e32 v197, s7, v126
	ds_read_b32 v95, v95
	ds_read_b32 v200, v197
	s_waitcnt lgkmcnt(2)
	v_add_f32_e32 v45, v45, v52
	v_max_f32_e64 v52, -v45, 0
	v_mul_f32_e64 v45, |v45|, s1
	v_exp_f32_e32 v45, v45
	s_waitcnt lgkmcnt(1)
	v_add_f32_e32 v43, v43, v95
	v_mul_f32_e32 v94, 0xbfb8aa3b, v94
	v_mul_f32_e32 v43, 0xbfb8aa3b, v43
	v_add_f32_e32 v45, 1.0, v45

; __device__ __forceinline__ float sigmoidf_(float x) { return __builtin_amdgcn_rcpf(1.0f + __expf(-x)); }
; __device__ __forceinline__ void rwkv_chunk_group(Frame& F, int bc, unsigned long long& tsub) {
;     ...
;             const float ic = sigmoidf_(a0 + al);
	v_exp_f32_e32 v94, v94
	v_exp_f32_e32 v43, v43


; __device__ __forceinline__ float sigmoidf_(float x) { return __builtin_amdgcn_rcpf(1.0f + __expf(-x)); }
; __device__ __forceinline__ void rwkv_chunk_group(Frame& F, int bc, unsigned long long& tsub) {
;     ...
;             const float z = -(w0 + wl); const float sp = fmaxf(z, 0.f) + __logf(1.f + __expf(-fabsf(z)));
;             const float lgd = -__expf(-sp - 0.5f);
;             const float ic = sigmoidf_(a0 + al);
	v_log_f32_e32 v45, v45
	v_add_f32_e32 v94, 1.0, v94
	v_add_f32_e32 v43, 1.0, v43
	v_rcp_f32_e32 v94, v94
	v_mul_f32_e32 v197, 0x3f317217, v45
	v_fma_f32 v197, v45, s9, -v197
	v_fmac_f32_e32 v197, 0x3377d1cf, v45
	v_fmac_f32_e32 v197, 0x3f317217, v45

; __device__ __forceinline__ float sigmoidf_(float x) { return __builtin_amdgcn_rcpf(1.0f + __expf(-x)); }
; __device__ __forceinline__ void rwkv_chunk_group(Frame& F, int bc, unsigned long long& tsub) {
;     ...
;             const float ic = sigmoidf_(a0 + al);
;             const float kv = k * k_k; const float kq = k * (1.f + (ic - 1.f) * k_a);
;             kkv[tt] = kv; icv[tt] = ic; sq[tt] = kv * kv; bq[tt] = r * kq * r_k;
;             rr[tt] = r; kp[tt] = kq; vv[tt] = v; run += lgd; ld[tt] = run; ggv[tt] = gl;
	v_rcp_f32_e32 v95, v43
	v_sub_f32_e32 v192, v190, v192
	v_mov_b32_e32 v45, v197


; __device__ __forceinline__ void wave_sum8(float (&x)[8]) {
;     const float y0 = swap32_add(x[0], x[4]), y1 = swap32_add(x[1], x[5]), y2 = swap32_add(x[2], x[6]), y3 = swap32_add(x[3], x[7]);
;     float z0 = swap16_add(y0, y2), z1 = swap16_add(y1, y3);
;     z0 = dpp_add(z0, 0); z1 = dpp_add(z1, 0); z0 = dpp_add(z0, 1); z1 = dpp_add(z1, 1); z0 = dpp_add(z0, 2); z1 = dpp_add(z1, 2); z0 = dpp_add(z0, 3); z1 = dpp_add(z1, 3);
;     const int i0 = __builtin_bit_cast(int, z0), i1 = __builtin_bit_cast(int, z1);
;     x[0] = __builtin_bit_cast(float, __builtin_amdgcn_readlane(i0, 0));  x[2] = __builtin_bit_cast(float, __builtin_amdgcn_readlane(i0, 16));
;     x[4] = __builtin_bit_cast(float, __builtin_amdgcn_readlane(i0, 32)); x[6] = __builtin_bit_cast(float, __builtin_amdgcn_readlane(i0, 48));
;     x[1] = __builtin_bit_cast(float, __builtin_amdgcn_readlane(i1, 0));  x[3] = __builtin_bit_cast(float, __builtin_amdgcn_readlane(i1, 16));
;     x[5] = __builtin_bit_cast(float, __builtin_amdgcn_readlane(i1, 32)); x[7] = __builtin_bit_cast(float, __builtin_amdgcn_readlane(i1, 48));
; }
; __device__ __forceinline__ void rwkv_chunk_group(Frame& F, int bc, unsigned long long& tsub) {
;     ...
;             const float kv = k * k_k; const float kq = k * (1.f + (ic - 1.f) * k_a);
;             kkv[tt] = kv; icv[tt] = ic; sq[tt] = kv * kv; bq[tt] = r * kq * r_k;
;             rr[tt] = r; kp[tt] = kq; vv[tt] = v; run += lgd; ld[tt] = run; ggv[tt] = gl;
;         }
;         wave_sum8(sq); wave_sum8(bq);
; #pragma unroll
;         for (int tt = 0; tt < 8; ++tt) { const float kn = kkv[tt] * __builtin_amdgcn_rsqf(fmaxf(sq[tt], 1e-24f));
;             aa[tt] = -kn; bb[tt] = kn * icv[tt]; vbv[tt] = bq[tt] * vv[tt]; }
;         *(LAS float*)(L + L_GT + (w * 64 + ch) * 4) = run;
;         *(GAS v4u*)(VBp + ch * 64 + tb) = (v4u){pk2(vbv[0], vbv[1]), pk2(vbv[2], vbv[3]), pk2(vbv[4], vbv[5]), pk2(vbv[6], vbv[7])};
;         *(GAS v4u*)(Gp + ch * 64 + tb) = (v4u){pk2(ggv[0], ggv[1]), pk2(ggv[2], ggv[3]), pk2(ggv[4], ggv[5]), pk2(ggv[6], ggv[7])};
;         if (hh + 1 < RW_H) {
;             const bool has = (c * CH + tb > 0);
; #pragma unroll
;             for (int tt = 0; tt < 9; ++tt) { const size_t off = (size_t)(row0 + tb + tt - 1) * PRW + hnext * 64 + ch;
;                 if (tt > 0 || has) { raw[tt][0] = P[off]; raw[tt][1] = P[off + 512]; raw[tt][2] = P[off + 1024]; } }
;         }
	v_add_f32_e32 v45, v52, v45
	v_sub_f32_e32 v45, -0.5, v45
	v_mul_f32_e32 v45, 0x3fb8aa3b, v45
	v_exp_f32_e32 v45, v45
	s_nop 0
	v_mul_f32_e32 v100, v80, v44
	v_mul_f32_e32 v101, v81, v44
	v_mul_f32_e32 v80, v98, v44
	v_mul_f32_e32 v81, v99, v44
	v_mul_f32_e32 v196, v100, v100
	v_mul_f32_e32 v197, v101, v101
	v_mul_f32_e32 v98, v80, v80
	v_mul_f32_e32 v99, v81, v81
	v_sub_f32_e32 v52, v192, v45
	s_nop 0
	v_permlane32_swap_b32_e32 v196, v98
	v_permlane32_swap_b32_e32 v197, v99
	v_add_f32_e32 v196, v196, v98
	v_add_f32_e32 v197, v197, v99
	v_lshlrev_b32_e32 v98, 16, v165
	v_and_b32_e32 v99, 0xffff0000, v165
	v_pk_mov_b32 v[96:97], v[96:97], v[98:99] op_sel:[1,0]
	v_mul_f32_e32 v88, v88, v44
	v_mul_f32_e32 v89, v89, v44
	v_add_f32_e64 v96, v96, -v98
	v_add_f32_e64 v97, v97, -v99
	v_mul_f32_e32 v198, v88, v88
	v_mul_f32_e32 v199, v89, v89
	v_fma_f32 v43, v97, v42, v99
	v_fma_f32 v42, v96, v42, v98
	v_add_f32_e64 v98, v94, -1.0
	v_add_f32_e64 v99, v95, -1.0
	v_mul_f32_e32 v45, v43, v44
	v_mul_f32_e32 v44, v42, v44
	v_fma_f32 v98, v46, v98, 1.0
	v_fma_f32 v99, v46, v99, 1.0
	v_mul_f32_e32 v42, v42, v98
	v_mul_f32_e32 v43, v43, v99
	v_mul_f32_e32 v96, v44, v44
	v_mul_f32_e32 v97, v45, v45
	v_mul_f32_e32 v46, v188, v42
	v_mul_f32_e32 v46, v103, v46
	s_nop 1
	v_permlane32_swap_b32_e32 v187, v46
	v_add_f32_e32 v46, v187, v46
	v_mul_f32_e32 v98, v191, v43
	s_nop 0
	v_permlane16_swap_b32_e32 v201, v46
	v_mul_f32_e32 v98, v103, v98
	v_add_f32_e32 v46, v201, v46
	s_nop 0
	v_permlane32_swap_b32_e32 v186, v98
	v_add_f32_dpp v46, v46, v46 quad_perm:[1,0,3,2] row_mask:0xf bank_mask:0xf bound_ctrl:1
	v_add_f32_e32 v98, v186, v98
	s_nop 1
	v_permlane16_swap_b32_e32 v195, v98
	v_add_f32_dpp v46, v46, v46 quad_perm:[2,3,0,1] row_mask:0xf bank_mask:0xf bound_ctrl:1
	v_add_f32_e32 v98, v195, v98
	v_permlane32_swap_b32_e32 v198, v96
	v_add_f32_dpp v46, v46, v46 row_half_mirror row_mask:0xf bank_mask:0xf bound_ctrl:1
	v_permlane32_swap_b32_e32 v199, v97
	s_nop 0
	v_add_f32_dpp v46, v46, v46 row_mirror row_mask:0xf bank_mask:0xf bound_ctrl:1
	v_add_f32_dpp v98, v98, v98 quad_perm:[1,0,3,2] row_mask:0xf bank_mask:0xf bound_ctrl:1
	v_readlane_b32 s14, v46, 0
	v_readlane_b32 s64, v46, 16
	v_readlane_b32 s72, v46, 32
	v_readlane_b32 s96, v46, 48
	v_add_f32_e32 v46, v198, v96
	v_add_f32_e32 v96, v199, v97
	v_add_f32_dpp v98, v98, v98 quad_perm:[2,3,0,1] row_mask:0xf bank_mask:0xf bound_ctrl:1
	v_permlane16_swap_b32_e32 v196, v46
	v_permlane16_swap_b32_e32 v197, v96
	v_add_f32_dpp v98, v98, v98 row_half_mirror row_mask:0xf bank_mask:0xf bound_ctrl:1
	v_add_f32_e32 v46, v196, v46
	v_add_f32_e32 v96, v197, v96
	v_add_f32_dpp v98, v98, v98 row_mirror row_mask:0xf bank_mask:0xf bound_ctrl:1
	v_add_f32_dpp v46, v46, v46 quad_perm:[1,0,3,2] row_mask:0xf bank_mask:0xf bound_ctrl:1
	v_add_f32_dpp v96, v96, v96 quad_perm:[1,0,3,2] row_mask:0xf bank_mask:0xf bound_ctrl:1
	v_readlane_b32 s73, v98, 32
	v_add_f32_dpp v46, v46, v46 quad_perm:[2,3,0,1] row_mask:0xf bank_mask:0xf bound_ctrl:1
	v_add_f32_dpp v96, v96, v96 quad_perm:[2,3,0,1] row_mask:0xf bank_mask:0xf bound_ctrl:1
	v_readlane_b32 s15, v98, 0
	v_readlane_b32 s65, v98, 16
	v_readlane_b32 s97, v98, 48
	v_add_f32_dpp v46, v46, v46 row_half_mirror row_mask:0xf bank_mask:0xf bound_ctrl:1
	v_add_f32_dpp v96, v96, v96 row_half_mirror row_mask:0xf bank_mask:0xf bound_ctrl:1
	v_mul_f32_e64 v196, v84, s72
	v_mul_f32_e64 v197, v85, s73
	s_lshl_b64 s[72:73], s[66:67], 13
	v_mul_f32_e64 v98, v36, s14
	v_mul_f32_e64 v99, v37, s15
	v_mul_f32_e64 v186, v76, s64
	v_mul_f32_e64 v187, v77, s65
	v_add_f32_dpp v46, v46, v46 row_mirror row_mask:0xf bank_mask:0xf bound_ctrl:1
	v_add_f32_dpp v96, v96, v96 row_mirror row_mask:0xf bank_mask:0xf bound_ctrl:1
	v_mul_f32_e64 v198, v92, s96
	v_mul_f32_e64 v199, v93, s97
	v_readlane_b32 s15, v254, 39
	s_cmp_eq_u32 s68, 7
	v_readlane_b32 s93, v46, 0
	v_readlane_b32 s71, v46, 16
	v_readlane_b32 s69, v46, 32
	v_readlane_b32 s64, v46, 48
	v_readlane_b32 s14, v96, 0
	v_readlane_b32 s77, v96, 16
	v_readlane_b32 s70, v96, 32
	v_readlane_b32 s65, v96, 48
	v_add_u32_e32 v46, s15, v105
	v_cvt_pk_bf16_f32 v96, v98, v99
	v_cvt_pk_bf16_f32 v97, v186, v187
	v_cvt_pk_bf16_f32 v98, v196, v197
	v_cvt_pk_bf16_f32 v99, v198, v199
	v_lshl_add_u64 v[186:187], v[62:63], 0, s[72:73]
	s_cselect_b64 s[96:97], -1, 0
	ds_write_b32 v46, v52
	global_store_dwordx4 v[186:187], v[96:99], off
	s_and_b64 vcc, exec, s[96:97]
	s_nop 0
	v_cvt_pk_bf16_f32 v96, v47, v177
	v_cvt_pk_bf16_f32 v97, v182, v185
	v_cvt_pk_bf16_f32 v98, v189, v193
	s_waitcnt lgkmcnt(1)
	v_cvt_pk_bf16_f32 v99, v194, v200
	v_lshl_add_u64 v[46:47], v[64:65], 0, s[72:73]
	global_store_dwordx4 v[46:47], v[96:99], off
	s_cbranch_vccnz .LBB0_1416
	v_readlane_b32 s72, v254, 60
	s_lshl_b32 s94, s13, 7
	v_readlane_b32 s73, v254, 61
	v_lshl_add_u64 v[46:47], v[56:57], 0, s[94:95]
	s_andn2_b64 vcc, exec, s[72:73]
	s_cbranch_vccnz .LBB0_1415
	v_readlane_b32 s72, v254, 62
	v_readlane_b32 s73, v254, 63
	s_nop 1
	v_lshl_add_u64 v[96:97], v[46:47], 0, s[72:73]
	global_load_ushort v153, v[96:97], off
	global_load_ushort v202, v[96:97], off offset:1024
	global_load_ushort v215, v[96:97], off offset:2048

; #define LAS __attribute__((address_space(3)))
; __device__ __forceinline__ void rwkv_chunk_group(Frame& F, int bc, unsigned long long& tsub) {
;     ...
;         float offs = 0.f, tot = 0.f;
; #pragma unroll
;         for (int g = 0; g < 8; ++g) { const float x = *(const LAS float*)(L + L_GT + (g * 64 + ch) * 4); if (g < w) offs += x; tot += x; }
;         const float etot = __expf(tot);
.LBB0_1418:
	v_cndmask_b32_e64 v182, v185, 0, s[82:83]
	v_readlane_b32 s66, v254, 40
	v_add_f32_e32 v47, v47, v182
	v_readlane_b32 s67, v254, 41

; #define GAS __attribute__((address_space(1)))
; #define LAS __attribute__((address_space(3)))
; __device__ __forceinline__ void rwkv_chunk_group(Frame& F, int bc, unsigned long long& tsub) {
;     ...
;         for (int tt = 0; tt < 8; ++tt) { const float kn = kkv[tt] * __builtin_amdgcn_rsqf(fmaxf(sq[tt], 1e-24f));
;             aa[tt] = -kn; bb[tt] = kn * icv[tt]; vbv[tt] = bq[tt] * vv[tt]; }
;         *(LAS float*)(L + L_GT + (w * 64 + ch) * 4) = run;
;         *(GAS v4u*)(VBp + ch * 64 + tb) = (v4u){pk2(vbv[0], vbv[1]), pk2(vbv[2], vbv[3]), pk2(vbv[4], vbv[5]), pk2(vbv[6], vbv[7])};
;         *(GAS v4u*)(Gp + ch * 64 + tb) = (v4u){pk2(ggv[0], ggv[1]), pk2(ggv[2], ggv[3]), pk2(ggv[4], ggv[5]), pk2(ggv[6], ggv[7])};
;         if (hh + 1 < RW_H) {
;             const bool has = (c * CH + tb > 0);
; #pragma unroll
;             for (int tt = 0; tt < 9; ++tt) { const size_t off = (size_t)(row0 + tb + tt - 1) * PRW + hnext * 64 + ch;
;                 if (tt > 0 || has) { raw[tt][0] = P[off]; raw[tt][1] = P[off + 512]; raw[tt][2] = P[off + 1024]; } }
;         }
;         LBAR();
;         float offs = 0.f, tot = 0.f;
; #pragma unroll
;         for (int g = 0; g < 8; ++g) { const float x = *(const LAS float*)(L + L_GT + (g * 64 + ch) * 4); if (g < w) offs += x; tot += x; }
;         const float etot = __expf(tot);
;         if (w == 0) *(LAS float*)(L + L_WC + ch * 4) = etot;
;         unsigned patt[4], pvt[4], pbh[4], pkh[4]; float hAt = 0.f, hBh = 0.f, hKh = 0.f;
;         float e_ex = __expf(offs);
; #pragma unroll
;         for (int tt = 0; tt < 8; ++tt) { const int t = tb + tt; const float cl = offs + ld[tt];
;             const float e_in = __expf(cl), e_inv = __builtin_amdgcn_rcpf(e_in), e_hat = etot * e_inv;
;             const float At = aa[tt] * e_ex, Bt = bb[tt] * e_inv, Kt = kp[tt] * e_inv, Rt = rr[tt] * e_in, Bh = bb[tt] * e_hat, Kh = kp[tt] * e_hat; e_ex = e_in;
;             *(LAS bf16*)(L + L_AT + t * LD + ch * 2) = (bf16)f2bf(At); *(LAS bf16*)(L + L_BT + t * LD + ch * 2) = (bf16)f2bf(Bt);
;             *(LAS bf16*)(L + L_KT + t * LD + ch * 2) = (bf16)f2bf(Kt); *(LAS bf16*)(L + L_RT + t * LD + ch * 2) = (bf16)f2bf(Rt);
;             if (tt & 1) { patt[tt >> 1] = pk2(hAt, At); pvt[tt >> 1] = pk2(vv[tt - 1], vv[tt]); pbh[tt >> 1] = pk2(hBh, Bh); pkh[tt >> 1] = pk2(hKh, Kh); }
;             hAt = At; hBh = Bh; hKh = Kh;
	s_mov_b32 s17, s16
	v_cndmask_b32_e64 v47, v182, v47, s[66:67]
	v_readlane_b32 s66, v254, 42
	v_add_f32_e32 v102, v102, v47
	v_readlane_b32 s67, v254, 43
	s_nop 1
	v_cndmask_b32_e64 v47, v47, v102, s[66:67]
	v_readlane_b32 s66, v254, 44
	v_add_f32_e32 v102, v103, v47
	v_readlane_b32 s67, v254, 45
	s_nop 1
	v_cndmask_b32_e64 v47, v47, v102, s[66:67]
	v_readlane_b32 s66, v254, 46
	v_add_f32_e32 v98, v98, v47
	v_readlane_b32 s67, v254, 47
	s_nop 1
	v_cndmask_b32_e64 v47, v47, v98, s[66:67]
	v_readlane_b32 s66, v254, 48
	v_add_f32_e32 v98, v99, v47
	v_readlane_b32 s67, v254, 49
	v_max_f32_e64 v99, s77, s77
	v_max_f32_e32 v99, 0x179abe15, v99
	v_cndmask_b32_e64 v47, v47, v98, s[66:67]
	v_readlane_b32 s66, v254, 50
	v_max_f32_e64 v98, s71, s71
	v_add_f32_e32 v96, v96, v47
	v_readlane_b32 s67, v254, 51
	v_max_f32_e32 v98, 0x179abe15, v98
	v_rsq_f32_e32 v98, v98
	v_cndmask_b32_e64 v47, v47, v96, s[66:67]
	v_rsq_f32_e32 v99, v99
	v_add_f32_e32 v102, v97, v47
	v_max_f32_e64 v97, s14, s14
	v_readlane_b32 s14, v254, 53
	v_readlane_b32 s15, v254, 54
	v_mul_f32_e32 v88, v88, v98
	v_mul_f32_e32 v89, v89, v99
	v_max_f32_e64 v98, s69, s69
	v_cndmask_b32_e64 v47, v47, v102, s[14:15]
	v_max_f32_e64 v99, s70, s70
	v_add_f32_e32 v102, v177, v47
	v_max_f32_e32 v98, 0x179abe15, v98
	v_max_f32_e32 v99, 0x179abe15, v99
	v_mul_f32_e32 v102, 0x3fb8aa3b, v102
	v_max_f32_e64 v96, s93, s93
	v_rsq_f32_e32 v98, v98
	v_rsq_f32_e32 v99, v99
	v_exp_f32_e32 v103, v102
	v_max_f32_e32 v96, 0x179abe15, v96
	v_max_f32_e32 v97, 0x179abe15, v97
	v_rsq_f32_e32 v96, v96
	v_rsq_f32_e32 v97, v97
	v_mul_f32_e32 v98, v80, v98
	v_mul_f32_e32 v99, v81, v99
	v_rcp_f32_e32 v80, v103
	v_mul_f32_e32 v81, 0x3fb8aa3b, v47
	v_mul_f32_e32 v96, v100, v96
	v_mul_f32_e32 v97, v101, v97
	v_exp_f32_e32 v102, v81
	v_mul_f32_e32 v38, v38, v96
	v_mul_f32_e32 v39, v39, v97
	s_mul_i32 s14, s16, 0x480
	v_mul_f32_e32 v81, v38, v80
	v_mul_f32_e32 v186, v86, v98
	v_mul_f32_e32 v187, v87, v99
	v_mul_f32_e32 v86, v40, v80
	v_mul_f32_e32 v87, v173, v103
	v_cvt_pk_bf16_f32 v81, v81, s0
	v_add_u32_e32 v173, s14, v58
	ds_write_b16 v173, v81 offset:9216
	v_cvt_pk_bf16_f32 v81, v86, s0
	v_add_f32_e32 v86, v176, v47
	v_mul_f32_e32 v86, 0x3fb8aa3b, v86
	v_max_f32_e64 v100, s64, s64
	v_max_f32_e64 v101, s65, s65
	v_exp_f32_e32 v176, v86
	v_max_f32_e32 v100, 0x179abe15, v100
	v_max_f32_e32 v101, 0x179abe15, v101
	v_rsq_f32_e32 v100, v100
	v_rsq_f32_e32 v101, v101
	ds_write_b16 v173, v81 offset:18432
	v_cvt_pk_bf16_f32 v81, v87, s0
	ds_write_b16 v173, v81 offset:27648
	v_rcp_f32_e32 v81, v176
	v_mul_f32_e32 v44, v44, v100
	v_mul_f32_e32 v45, v45, v101
	v_mul_f32_e64 v86, v102, -v96
	v_mul_f32_e64 v87, v103, -v97
	v_mul_f32_e32 v100, v94, v44
	v_mul_f32_e32 v101, v95, v45
	v_cvt_pk_bf16_f32 v94, v86, s0
	ds_write_b16 v173, v94
	v_mul_f32_e32 v94, v39, v81
	v_mul_f32_e32 v95, v41, v81
	v_cvt_pk_bf16_f32 v94, v94, s0
	v_mul_f32_e32 v96, v174, v176
	ds_write_b16 v173, v94 offset:9360
	v_cvt_pk_bf16_f32 v94, v95, s0
	ds_write_b16 v173, v94 offset:18576
	v_cvt_pk_bf16_f32 v94, v96, s0
	ds_write_b16 v173, v94 offset:27792
	v_add_f32_e32 v94, v179, v47
	v_mul_f32_e32 v94, 0x3fb8aa3b, v94
	v_exp_f32_e32 v177, v94
	v_mul_f32_e32 v82, v82, v88
	v_mul_f32_e32 v83, v83, v89
	v_mul_f32_e32 v80, v46, v80
	v_mul_f32_e32 v81, v46, v81
	v_mul_f32_e32 v40, v40, v80
	v_mul_f32_e32 v41, v41, v81
	v_rcp_f32_e32 v96, v177
	v_mul_f32_e32 v94, v38, v80
	v_mul_f32_e32 v95, v39, v81
	v_cvt_pk_bf16_f32 v80, v36, v37
	v_cvt_pk_bf16_f32 v97, v87, s0
	v_mul_f32_e32 v36, v82, v96
	v_cvt_pk_bf16_f32 v36, v36, s0
	ds_write_b16 v173, v36 offset:9504
	v_add_f32_e32 v36, v181, v47
	v_mul_f32_e32 v36, 0x3fb8aa3b, v36
	v_exp_f32_e32 v36, v36
	ds_write_b16 v173, v97 offset:144
	v_mul_f32_e32 v37, v78, v96
	v_mul_f32_e32 v39, v175, v177
	v_rcp_f32_e32 v97, v36
	v_cvt_pk_bf16_f32 v37, v37, s0
	v_cvt_pk_bf16_f32 v38, v86, v87
	v_cvt_pk_bf16_f32 v86, v94, v95
	v_cvt_pk_bf16_f32 v94, v40, v41
	ds_write_b16 v173, v37 offset:18720
	v_cvt_pk_bf16_f32 v37, v39, s0
	v_mul_f32_e64 v40, v176, -v88
	v_mul_f32_e64 v41, v177, -v89
	ds_write_b16 v173, v37 offset:27936
	v_cvt_pk_bf16_f32 v37, v40, s0
	ds_write_b16 v173, v37 offset:288
	v_mul_f32_e32 v37, v83, v97
	v_mul_f32_e32 v39, v79, v97
	v_cvt_pk_bf16_f32 v37, v37, s0
	v_mul_f32_e32 v81, v178, v36
	ds_write_b16 v173, v37 offset:9648
	v_cvt_pk_bf16_f32 v37, v39, s0
	ds_write_b16 v173, v37 offset:18864
	v_cvt_pk_bf16_f32 v37, v81, s0
	ds_write_b16 v173, v37 offset:28080
	v_add_f32_e32 v37, v184, v47
	v_mul_f32_e32 v37, 0x3fb8aa3b, v37
	v_exp_f32_e32 v37, v37
	v_cvt_pk_bf16_f32 v39, v40, v41
	v_cvt_pk_bf16_f32 v87, v41, s0
	v_cvt_pk_bf16_f32 v81, v76, v77
	v_rcp_f32_e32 v40, v37
	v_mul_f32_e32 v77, v180, v37
	v_mul_f32_e64 v36, v36, -v98
	v_mul_f32_e64 v37, v37, -v99
	v_mul_f32_e32 v88, v46, v96
	v_mul_f32_e32 v89, v46, v97
	v_mul_f32_e32 v41, v186, v40
	v_mul_f32_e32 v76, v90, v40
	v_cvt_pk_bf16_f32 v41, v41, s0
	ds_write_b16 v173, v41 offset:9792
	v_cvt_pk_bf16_f32 v41, v76, s0
	v_add_f32_e32 v76, v190, v47
	v_mul_f32_e32 v76, 0x3fb8aa3b, v76
	v_exp_f32_e32 v76, v76
	ds_write_b16 v173, v41 offset:19008
	v_cvt_pk_bf16_f32 v41, v77, s0
	ds_write_b16 v173, v41 offset:28224
	v_rcp_f32_e32 v41, v76
	v_cvt_pk_bf16_f32 v77, v36, s0
	v_mul_f32_e32 v78, v78, v88
	v_mul_f32_e32 v79, v79, v89
	ds_write_b16 v173, v77 offset:576
	v_mul_f32_e32 v77, v187, v41
	v_cvt_pk_bf16_f32 v95, v78, v79
	v_mul_f32_e32 v78, v91, v41
	v_cvt_pk_bf16_f32 v77, v77, s0
	v_mul_f32_e32 v79, v183, v76
	ds_write_b16 v173, v77 offset:9936
	v_cvt_pk_bf16_f32 v77, v78, s0
	ds_write_b16 v173, v77 offset:19152
	v_cvt_pk_bf16_f32 v77, v79, s0
; __device__ __forceinline__ void rwkv_chunk_group(Frame& F, int bc, unsigned long long& tsub) {
;     ...
;         for (int tt = 0; tt < 8; ++tt) { const int t = tb + tt; const float cl = offs + ld[tt];
;             const float e_in = __expf(cl), e_inv = __builtin_amdgcn_rcpf(e_in), e_hat = etot * e_inv;
;             const float At = aa[tt] * e_ex, Bt = bb[tt] * e_inv, Kt = kp[tt] * e_inv, Rt = rr[tt] * e_in, Bh = bb[tt] * e_hat, Kh = kp[tt] * e_hat; e_ex = e_in;
;             *(LAS bf16*)(L + L_AT + t * LD + ch * 2) = (bf16)f2bf(At); *(LAS bf16*)(L + L_BT + t * LD + ch * 2) = (bf16)f2bf(Bt);
;             *(LAS bf16*)(L + L_KT + t * LD + ch * 2) = (bf16)f2bf(Kt); *(LAS bf16*)(L + L_RT + t * LD + ch * 2) = (bf16)f2bf(Rt);
;             if (tt & 1) { patt[tt >> 1] = pk2(hAt, At); pvt[tt >> 1] = pk2(vv[tt - 1], vv[tt]); pbh[tt >> 1] = pk2(hBh, Bh); pkh[tt >> 1] = pk2(hKh, Kh); }
;             hAt = At; hBh = Bh; hKh = Kh;
;         }
;         *(LAS v4u*)(L + L_ATT + ch * LD + tb * 2) = (v4u){patt[0], patt[1], patt[2], patt[3]};
;         *(LAS v4u*)(L + L_VT + ch * LD + tb * 2) = (v4u){pvt[0], pvt[1], pvt[2], pvt[3]};
;         *(LAS v4u*)(L + L_BH + ch * LD + tb * 2) = (v4u){pbh[0], pbh[1], pbh[2], pbh[3]};
;         *(LAS v4u*)(L + L_KH + ch * LD + tb * 2) = (v4u){pkh[0], pkh[1], pkh[2], pkh[3]};
;         LBAR();
;     }
;     TSUB(2);
; #pragma unroll
;     for (int q = 0; q < 2; ++q) { const int tw = 2 * w + q, p0 = 16 * (tw >> 2), q0 = 16 * (tw & 3);
;         f32x4 m = mm_tile(L + L_AT, LD, q0, L + L_BT, LD, p0, 2, Z4, fr, fq);
;         f32x4 nak = mm_tile(L + L_KT, LD, q0, L + L_AT, LD, p0, 2, Z4, fr, fq);
;         f32x4 nrk = mm_tile(L + L_KT, LD, q0, L + L_RT, LD, p0, 2, Z4, fr, fq);
;         f32x4 nrb = mm_tile(L + L_BT, LD, q0, L + L_RT, LD, p0, 2, Z4, fr, fq);
;         f32x4 tt;
;         const int p = p0 + fr;
; #pragma unroll
;         for (int v = 0; v < 4; ++v) { const int qq = q0 + 4 * fq + v;
;             if (!(p < qq)) m[v] = 0.f;
;             if (!(qq < p)) nak[v] = 0.f;
;             if (!(qq <= p)) { nrk[v] = 0.f; nrb[v] = 0.f; }
;             tt[v] = (p == qq) ? 1.f : 0.f; }
;         const int o = p * LD + (q0 + 4 * fq) * 2;
;         st4_lds(L + L_M + o, m); st4t_lds(L + L_MT, p, q0 + 4 * fq, m); st4_lds(L + L_NAK + o, nak); st4_lds(L + L_NRK + o, nrk); st4_lds(L + L_NRB + o, nrb); st4_lds(L + L_TT + o, tt);
;     }
;     LBAR();
	ds_write_b16 v173, v77 offset:28368
	v_add_f32_e32 v77, v192, v47
	v_mul_f32_e32 v77, 0x3fb8aa3b, v77
	v_exp_f32_e32 v77, v77
	v_mul_f32_e32 v40, v46, v40
	v_mul_f32_e32 v41, v46, v41
	v_mul_f32_e32 v82, v82, v88
	v_mul_f32_e32 v83, v83, v89
	v_mul_f32_e32 v78, v90, v40
	v_mul_f32_e32 v79, v91, v41
	v_mul_f32_e32 v88, v186, v40
	v_mul_f32_e32 v89, v187, v41
	v_cvt_pk_bf16_f32 v40, v36, v37
	v_rcp_f32_e32 v36, v77
	ds_write_b16 v173, v87 offset:432
	v_cvt_pk_bf16_f32 v87, v82, v83
	v_cvt_pk_bf16_f32 v82, v37, s0
	v_mul_f32_e32 v37, v100, v36
	v_mul_f32_e32 v41, v42, v36
	v_cvt_pk_bf16_f32 v37, v37, s0
	ds_write_b16 v173, v37 offset:10080
	v_cvt_pk_bf16_f32 v37, v41, s0
	v_add_f32_e32 v41, v52, v47
	v_mul_f32_e32 v41, 0x3fb8aa3b, v41
	v_exp_f32_e32 v41, v41
	v_cvt_pk_bf16_f32 v96, v78, v79
	v_mul_f32_e32 v78, v188, v77
	ds_write_b16 v173, v37 offset:19296
	v_cvt_pk_bf16_f32 v37, v78, s0
	ds_write_b16 v173, v37 offset:28512
	v_rcp_f32_e32 v37, v41
	v_mul_f32_e64 v44, v76, -v44
	v_mul_f32_e64 v45, v77, -v45
	v_mul_f32_e32 v41, v191, v41
	v_cvt_pk_bf16_f32 v47, v44, s0
	ds_write_b16 v173, v47 offset:864
	v_mul_f32_e32 v47, v101, v37
	v_mul_f32_e32 v52, v43, v37
	v_cvt_pk_bf16_f32 v47, v47, s0
	ds_write_b16 v173, v47 offset:10224
	v_cvt_pk_bf16_f32 v47, v52, s0
	v_cvt_pk_bf16_f32 v41, v41, s0
	v_mul_f32_e32 v36, v46, v36
	v_mul_f32_e32 v37, v46, v37
	v_cvt_pk_bf16_f32 v76, v45, s0
	ds_write_b16 v173, v41 offset:28656
	v_mul_f32_e32 v42, v42, v36
	v_mul_f32_e32 v43, v43, v37
	v_mul_f32_e32 v36, v100, v36
	v_mul_f32_e32 v37, v101, v37
	v_cvt_pk_bf16_f32 v41, v44, v45
	ds_write_b16 v173, v82 offset:720
	v_cvt_pk_bf16_f32 v82, v84, v85
	v_cvt_pk_bf16_f32 v88, v88, v89
	ds_write_b16 v173, v76 offset:1008
	ds_write_b16 v173, v47 offset:19440
	v_cvt_pk_bf16_f32 v97, v42, v43
	v_cvt_pk_bf16_f32 v89, v36, v37
	v_cvt_pk_bf16_f32 v83, v92, v93
	ds_write_b128 v141, v[38:41] offset:36864
	ds_write_b128 v141, v[80:83] offset:46080
	ds_write_b128 v141, v[86:89] offset:55296
	ds_write_b128 v141, v[94:97] offset:64512
	s_waitcnt lgkmcnt(0)
	s_barrier
	v_add_u32_e32 v76, v106, v110
	v_add_u32_e32 v77, v106, v128
	v_add_u32_e32 v97, 0x12000, v127
	v_add_u32_e32 v98, 0x12000, v129
	ds_read_b128 v[176:179], v76 offset:0
	ds_read_b128 v[224:227], v107 offset:9216
	ds_read_b128 v[184:187], v76 offset:18432
	ds_read_b128 v[232:235], v107 offset:0
	ds_read_b128 v[240:243], v107 offset:27648
	ds_read_b128 v[192:195], v76 offset:9216
	ds_read_b128 v[180:183], v76 offset:64
	ds_read_b128 v[228:231], v107 offset:9280
	ds_read_b128 v[188:191], v76 offset:18496
	ds_read_b128 v[236:239], v107 offset:64
	ds_read_b128 v[244:247], v107 offset:27712
	ds_read_b128 v[196:199], v76 offset:9280
	s_waitcnt lgkmcnt(10)
	v_mfma_f32_16x16x32_bf16 v[78:81], v[176:179], v[224:227], 0
	s_waitcnt lgkmcnt(8)
	v_mfma_f32_16x16x32_bf16 v[82:85], v[184:187], v[232:235], 0
	s_waitcnt lgkmcnt(7)
	v_mfma_f32_16x16x32_bf16 v[86:89], v[184:187], v[240:243], 0
	s_waitcnt lgkmcnt(6)
	v_mfma_f32_16x16x32_bf16 v[90:93], v[192:195], v[240:243], 0
	s_waitcnt lgkmcnt(4)
	v_mfma_f32_16x16x32_bf16 v[78:81], v[180:183], v[228:231], v[78:81]
	s_waitcnt lgkmcnt(2)
	v_mfma_f32_16x16x32_bf16 v[82:85], v[188:191], v[236:239], v[82:85]
	s_waitcnt lgkmcnt(1)
	v_mfma_f32_16x16x32_bf16 v[86:89], v[188:191], v[244:247], v[86:89]
	s_waitcnt lgkmcnt(0)
	v_mfma_f32_16x16x32_bf16 v[90:93], v[196:199], v[244:247], v[90:93]
	ds_read_b128 v[176:179], v77 offset:0
	ds_read_b128 v[184:187], v77 offset:18432
	ds_read_b128 v[192:195], v77 offset:9216
	ds_read_b128 v[180:183], v77 offset:64
	ds_read_b128 v[188:191], v77 offset:18496
	ds_read_b128 v[196:199], v77 offset:9280
	s_nop 1
	v_cndmask_b32_e64 v78, 0, v78, s[48:49]
	v_cndmask_b32_e64 v79, v79, 0, s[50:51]
	v_cndmask_b32_e64 v80, 0, v80, s[52:53]
	v_cndmask_b32_e64 v81, 0, v81, s[54:55]
	v_cndmask_b32_e64 v82, 0, v82, s[50:51]
	v_cndmask_b32_e64 v83, 0, v83, s[40:41]
	v_cndmask_b32_e64 v84, 0, v84, s[38:39]
	v_cndmask_b32_e64 v85, 0, v85, s[36:37]
	v_cndmask_b32_e64 v86, v86, 0, s[48:49]
	v_cndmask_b32_e64 v87, 0, v87, s[50:51]
	v_cndmask_b32_e64 v88, v88, 0, s[52:53]
	v_cndmask_b32_e64 v89, v89, 0, s[54:55]
	v_cndmask_b32_e64 v90, v90, 0, s[48:49]
	v_cndmask_b32_e64 v91, 0, v91, s[50:51]
	v_cndmask_b32_e64 v92, v92, 0, s[52:53]
	v_cndmask_b32_e64 v93, v93, 0, s[54:55]
	v_cvt_pk_bf16_f32 v78, v78, v79
	v_cvt_pk_bf16_f32 v79, v80, v81
	v_cvt_pk_bf16_f32 v82, v82, v83
	v_cvt_pk_bf16_f32 v83, v84, v85
	v_cvt_pk_bf16_f32 v86, v86, v87
	v_cvt_pk_bf16_f32 v87, v88, v89
	v_cvt_pk_bf16_f32 v90, v90, v91
	v_cvt_pk_bf16_f32 v91, v92, v93
	ds_write_b64 v97, v[78:79]
	ds_write_b64 v97, v[82:83] offset:27648
	ds_write_b64 v97, v[86:87] offset:36864
	ds_write_b64 v97, v[90:91] offset:46080
	ds_write_b64 v97, v[60:61] offset:18432
	s_waitcnt lgkmcnt(10)
	v_mfma_f32_16x16x32_bf16 v[36:39], v[176:179], v[224:227], 0
	s_waitcnt lgkmcnt(9)
	v_mfma_f32_16x16x32_bf16 v[40:43], v[184:187], v[232:235], 0
	s_waitcnt lgkmcnt(9)
	v_mfma_f32_16x16x32_bf16 v[44:47], v[184:187], v[240:243], 0
	s_waitcnt lgkmcnt(8)
	v_mfma_f32_16x16x32_bf16 v[100:103], v[192:195], v[240:243], 0
	s_waitcnt lgkmcnt(7)
	v_mfma_f32_16x16x32_bf16 v[36:39], v[180:183], v[228:231], v[36:39]
	s_waitcnt lgkmcnt(6)
	v_mfma_f32_16x16x32_bf16 v[40:43], v[188:191], v[236:239], v[40:43]
	s_waitcnt lgkmcnt(6)
	v_mfma_f32_16x16x32_bf16 v[44:47], v[188:191], v[244:247], v[44:47]
	s_waitcnt lgkmcnt(5)
	v_mfma_f32_16x16x32_bf16 v[100:103], v[196:199], v[244:247], v[100:103]
	s_nop 7
	v_cndmask_b32_e64 v36, 0, v36, s[56:57]
	v_cndmask_b32_e64 v37, v37, 0, s[58:59]
	v_cndmask_b32_e64 v38, 0, v38, s[60:61]
	v_cndmask_b32_e64 v39, 0, v39, s[62:63]
	v_cndmask_b32_e64 v40, 0, v40, s[58:59]
	v_cndmask_b32_e64 v41, 0, v41, s[46:47]
	v_cndmask_b32_e64 v42, 0, v42, s[44:45]
	v_cndmask_b32_e64 v43, 0, v43, s[42:43]
	v_cndmask_b32_e64 v44, v44, 0, s[56:57]
	v_cndmask_b32_e64 v45, 0, v45, s[58:59]
	v_cndmask_b32_e64 v46, v46, 0, s[60:61]
	v_cndmask_b32_e64 v47, v47, 0, s[62:63]
	v_cndmask_b32_e64 v100, v100, 0, s[56:57]
	v_cndmask_b32_e64 v101, 0, v101, s[58:59]
	v_cndmask_b32_e64 v102, v102, 0, s[60:61]
	v_cndmask_b32_e64 v103, v103, 0, s[62:63]
	v_cvt_pk_bf16_f32 v36, v36, v37
	v_cvt_pk_bf16_f32 v37, v38, v39
	v_cvt_pk_bf16_f32 v40, v40, v41
	v_cvt_pk_bf16_f32 v41, v42, v43
	v_cvt_pk_bf16_f32 v44, v44, v45
	v_cvt_pk_bf16_f32 v45, v46, v47
	v_cvt_pk_bf16_f32 v100, v100, v101
	v_cvt_pk_bf16_f32 v101, v102, v103
	ds_write_b64 v98, v[36:37]
	ds_write_b64 v98, v[40:41] offset:27648
	ds_write_b64 v98, v[44:45] offset:36864
	ds_write_b64 v98, v[100:101] offset:46080
	ds_write_b64 v98, v[72:73] offset:18432

; #define LAS __attribute__((address_space(3)))
; __device__ __forceinline__ void st4_lds(LAS unsigned char* p, f32x4 v) { v2u w; w.x = pk2(v[0], v[1]); w.y = pk2(v[2], v[3]); *(LAS v2u*)p = w; }
; __device__ __forceinline__ f32x4 ld4_lds(const LAS unsigned char* p) { const v2u w = *(const LAS v2u*)p; return (f32x4){bflo(w.x), bfhi(w.x), bflo(w.y), bfhi(w.y)}; }
; #define LBAR() asm volatile("s_waitcnt lgkmcnt(0)\n\ts_barrier" ::: "memory")
; __device__ __forceinline__ f32x4 mm_tile(const LAS unsigned char* X, int ldx, int x0, const LAS unsigned char* Y, int ldy, int y0, int ksteps, f32x4 acc, int fr, int fq) {
;     const LAS unsigned char* xp = X + (x0 + fr) * ldx + fq * 16; const LAS unsigned char* yp = Y + (y0 + fr) * ldy + fq * 16;
;     for (int k = 0; k < ksteps; ++k) { const bf16x8 a = *(const LAS bf16x8*)(xp + k * 64), b = *(const LAS bf16x8*)(yp + k * 64); acc = __builtin_amdgcn_mfma_f32_16x16x32_bf16(a, b, acc, 0, 0, 0); }
;     return acc;
; __device__ __forceinline__ void rwkv_chunk_group(Frame& F, int bc, unsigned long long& tsub) {
;     ...
;     for (int it = 0; it < 6; ++it) {
;         const int rM = (it & 1) ? L_AT : L_M, rMT = (it & 1) ? L_BT : L_MT, rTT = (it & 1) ? L_KT : L_TT;
;         const int wM = (it & 1) ? L_M : L_AT, wMT = (it & 1) ? L_MT : L_BT, wTT = (it & 1) ? L_TT : L_KT;
; #pragma unroll
;         for (int q = 0; q < 2; ++q) { const int tw = 2 * w + q, p0 = 16 * (tw >> 2), q0 = 16 * (tw & 3); const int o = (p0 + fr) * LD + (q0 + 4 * fq) * 2;
;             f32x4 tn = Z4, mn = Z4;
;             if (q0 <= p0) { tn = mm_tile(L + rM, LD, q0, L + rTT, LD, p0, 2, ld4_lds(L + rTT + o), fr, fq);
;                           }
;             if (q0 >= p0 && it < 5) mn = mm_tile(L + rMT, LD, q0, L + rM, LD, p0, 2, Z4, fr, fq);
;             st4_lds(L + wTT + o, tn); if (it < 5) { st4_lds(L + wM + o, mn); st4t_lds(L + wMT, p0 + fr, q0 + 4 * fq, mn); } }
;         LBAR();
;     }
	s_waitcnt lgkmcnt(0)
	s_barrier
	v_mov_b32_e32 v78, v127
	v_mov_b32_e32 v79, v129
	v_add_u32_e32 v173, v106, v110
	v_add_u32_e32 v174, v106, v128
	v_add_u32_e32 v97, 0x12000, v127
	v_add_u32_e32 v98, 0x12000, v129
	v_mov_b32_e32 v102, 0
	v_mov_b32_e32 v103, 0
	v_add_u32_e32 v175, 0x12000, v173
	v_add_u32_e32 v96, 0x12000, v174
	s_and_b64 vcc, exec, s[78:79]
	s_cbranch_vccz .La2_FTFT
	s_and_b64 vcc, exec, s[84:85]
	s_cbranch_vccz .La2_TFTx
	ds_read_b64 v[242:243], v97 offset:18432
	ds_read_b128 v[176:179], v175 offset:0
	ds_read_b128 v[224:227], v132 offset:18432
	ds_read_b64_tr_b16 v[184:185], v253 offset:0
	ds_read_b64_tr_b16 v[186:187], v253 offset:576
	ds_read_b128 v[232:235], v132 offset:0
	ds_read_b64_tr_b16 v[192:193], v253 offset:32
	ds_read_b64_tr_b16 v[194:195], v253 offset:608
	ds_read_b128 v[180:183], v175 offset:64
	ds_read_b128 v[228:231], v132 offset:18496
	ds_read_b64_tr_b16 v[188:189], v253 offset:4608
	ds_read_b64_tr_b16 v[190:191], v253 offset:5184
	ds_read_b128 v[236:239], v132 offset:64
	ds_read_b64_tr_b16 v[196:197], v253 offset:4640
	ds_read_b64_tr_b16 v[198:199], v253 offset:5216
	s_waitcnt lgkmcnt(14)
	v_lshlrev_b32_e32 v240, 16, v242
	v_and_b32_e32 v241, 0xffff0000, v242
	v_lshlrev_b32_e32 v242, 16, v243
	v_and_b32_e32 v243, 0xffff0000, v243
	s_nop 1
	s_waitcnt lgkmcnt(12)
	v_mfma_f32_16x16x32_bf16 v[240:243], v[176:179], v[224:227], v[240:243]
	s_waitcnt lgkmcnt(9)
	v_mfma_f32_16x16x32_bf16 v[244:247], v[184:187], v[232:235], 0
	s_waitcnt lgkmcnt(7)
	v_mfma_f32_16x16x32_bf16 v[248:251], v[192:195], v[232:235], 0
	s_waitcnt lgkmcnt(5)
	v_mfma_f32_16x16x32_bf16 v[240:243], v[180:183], v[228:231], v[240:243]
	s_waitcnt lgkmcnt(2)
	v_mfma_f32_16x16x32_bf16 v[244:247], v[188:191], v[236:239], v[244:247]
	s_waitcnt lgkmcnt(0)
	v_mfma_f32_16x16x32_bf16 v[248:251], v[196:199], v[236:239], v[248:251]
	s_nop 7
	v_cvt_pk_bf16_f32 v176, v240, v241
	v_cvt_pk_bf16_f32 v177, v242, v243
	v_cvt_pk_bf16_f32 v184, v244, v245
	v_cvt_pk_bf16_f32 v185, v246, v247
	v_cvt_pk_bf16_f32 v192, v248, v249
	v_cvt_pk_bf16_f32 v193, v250, v251
	ds_write_b64 v127, v[176:177] offset:18432
	ds_write_b64 v127, v[184:185] offset:0
	ds_write_b64 v129, v[102:103] offset:18432
	ds_write_b64 v129, v[192:193] offset:0
	s_waitcnt lgkmcnt(0)
	s_barrier
	ds_read_b64 v[242:243], v127 offset:18432
	ds_read_b128 v[176:179], v173 offset:0
	ds_read_b128 v[224:227], v107 offset:18432
	ds_read_b64_tr_b16 v[184:185], v252 offset:0
	ds_read_b64_tr_b16 v[186:187], v252 offset:576
	ds_read_b128 v[232:235], v107 offset:0
	ds_read_b64_tr_b16 v[192:193], v252 offset:32
	ds_read_b64_tr_b16 v[194:195], v252 offset:608
	ds_read_b128 v[180:183], v173 offset:64
	ds_read_b128 v[228:231], v107 offset:18496
	ds_read_b64_tr_b16 v[188:189], v252 offset:4608
	ds_read_b64_tr_b16 v[190:191], v252 offset:5184
	ds_read_b128 v[236:239], v107 offset:64
	ds_read_b64_tr_b16 v[196:197], v252 offset:4640
	ds_read_b64_tr_b16 v[198:199], v252 offset:5216
	s_waitcnt lgkmcnt(14)
	v_lshlrev_b32_e32 v240, 16, v242
	v_and_b32_e32 v241, 0xffff0000, v242
	v_lshlrev_b32_e32 v242, 16, v243
	v_and_b32_e32 v243, 0xffff0000, v243
	s_nop 1
	s_waitcnt lgkmcnt(12)
	v_mfma_f32_16x16x32_bf16 v[240:243], v[176:179], v[224:227], v[240:243]
	s_waitcnt lgkmcnt(9)
	v_mfma_f32_16x16x32_bf16 v[244:247], v[184:187], v[232:235], 0
	s_waitcnt lgkmcnt(7)
	v_mfma_f32_16x16x32_bf16 v[248:251], v[192:195], v[232:235], 0
	s_waitcnt lgkmcnt(5)
	v_mfma_f32_16x16x32_bf16 v[240:243], v[180:183], v[228:231], v[240:243]
	s_waitcnt lgkmcnt(2)
	v_mfma_f32_16x16x32_bf16 v[244:247], v[188:191], v[236:239], v[244:247]
	s_waitcnt lgkmcnt(0)
	v_mfma_f32_16x16x32_bf16 v[248:251], v[196:199], v[236:239], v[248:251]
	s_nop 7
	v_cvt_pk_bf16_f32 v176, v240, v241
	v_cvt_pk_bf16_f32 v177, v242, v243
	v_cvt_pk_bf16_f32 v184, v244, v245
	v_cvt_pk_bf16_f32 v185, v246, v247
	v_cvt_pk_bf16_f32 v192, v248, v249
	v_cvt_pk_bf16_f32 v193, v250, v251
	ds_write_b64 v97, v[176:177] offset:18432
	ds_write_b64 v97, v[184:185] offset:0
	ds_write_b64 v98, v[192:193] offset:0
	s_waitcnt lgkmcnt(0)
	s_barrier
	ds_read_b64 v[242:243], v97 offset:18432
	ds_read_b128 v[176:179], v175 offset:0
	ds_read_b128 v[224:227], v132 offset:18432
	ds_read_b64_tr_b16 v[184:185], v253 offset:0
	ds_read_b64_tr_b16 v[186:187], v253 offset:576
	ds_read_b128 v[232:235], v132 offset:0
	ds_read_b64_tr_b16 v[192:193], v253 offset:32
	ds_read_b64_tr_b16 v[194:195], v253 offset:608
	ds_read_b128 v[180:183], v175 offset:64
	ds_read_b128 v[228:231], v132 offset:18496
	ds_read_b64_tr_b16 v[188:189], v253 offset:4608
	ds_read_b64_tr_b16 v[190:191], v253 offset:5184
	ds_read_b128 v[236:239], v132 offset:64
	ds_read_b64_tr_b16 v[196:197], v253 offset:4640
	ds_read_b64_tr_b16 v[198:199], v253 offset:5216
	s_waitcnt lgkmcnt(14)
	v_lshlrev_b32_e32 v240, 16, v242
	v_and_b32_e32 v241, 0xffff0000, v242
	v_lshlrev_b32_e32 v242, 16, v243
	v_and_b32_e32 v243, 0xffff0000, v243
	s_nop 1
	s_waitcnt lgkmcnt(12)
	v_mfma_f32_16x16x32_bf16 v[240:243], v[176:179], v[224:227], v[240:243]
	s_waitcnt lgkmcnt(9)
	v_mfma_f32_16x16x32_bf16 v[244:247], v[184:187], v[232:235], 0
	s_waitcnt lgkmcnt(7)
	v_mfma_f32_16x16x32_bf16 v[248:251], v[192:195], v[232:235], 0
	s_waitcnt lgkmcnt(5)
	v_mfma_f32_16x16x32_bf16 v[240:243], v[180:183], v[228:231], v[240:243]
	s_waitcnt lgkmcnt(2)
	v_mfma_f32_16x16x32_bf16 v[244:247], v[188:191], v[236:239], v[244:247]
	s_waitcnt lgkmcnt(0)
	v_mfma_f32_16x16x32_bf16 v[248:251], v[196:199], v[236:239], v[248:251]
	s_nop 7
	v_cvt_pk_bf16_f32 v176, v240, v241
	v_cvt_pk_bf16_f32 v177, v242, v243
	v_cvt_pk_bf16_f32 v184, v244, v245
	v_cvt_pk_bf16_f32 v185, v246, v247
	v_cvt_pk_bf16_f32 v192, v248, v249
	v_cvt_pk_bf16_f32 v193, v250, v251
	ds_write_b64 v127, v[176:177] offset:18432
	ds_write_b64 v127, v[184:185] offset:0
	ds_write_b64 v129, v[192:193] offset:0
	s_waitcnt lgkmcnt(0)
	s_barrier
; __device__ __forceinline__ void st4_lds(LAS unsigned char* p, f32x4 v) { v2u w; w.x = pk2(v[0], v[1]); w.y = pk2(v[2], v[3]); *(LAS v2u*)p = w; }
; __device__ __forceinline__ f32x4 ld4_lds(const LAS unsigned char* p) { const v2u w = *(const LAS v2u*)p; return (f32x4){bflo(w.x), bfhi(w.x), bflo(w.y), bfhi(w.y)}; }
; #define LBAR() asm volatile("s_waitcnt lgkmcnt(0)\n\ts_barrier" ::: "memory")
; __device__ __forceinline__ void rwkv_chunk_group(Frame& F, int bc, unsigned long long& tsub) {
;     ...
;     for (int it = 0; it < 6; ++it) {
;         const int rM = (it & 1) ? L_AT : L_M, rMT = (it & 1) ? L_BT : L_MT, rTT = (it & 1) ? L_KT : L_TT;
;         const int wM = (it & 1) ? L_M : L_AT, wMT = (it & 1) ? L_MT : L_BT, wTT = (it & 1) ? L_TT : L_KT;
; #pragma unroll
;         for (int q = 0; q < 2; ++q) { const int tw = 2 * w + q, p0 = 16 * (tw >> 2), q0 = 16 * (tw & 3); const int o = (p0 + fr) * LD + (q0 + 4 * fq) * 2;
;             f32x4 tn = Z4, mn = Z4;
;             if (q0 <= p0) { tn = mm_tile(L + rM, LD, q0, L + rTT, LD, p0, 2, ld4_lds(L + rTT + o), fr, fq);
;                           }
;             if (q0 >= p0 && it < 5) mn = mm_tile(L + rMT, LD, q0, L + rM, LD, p0, 2, Z4, fr, fq);
;             st4_lds(L + wTT + o, tn); if (it < 5) { st4_lds(L + wM + o, mn); st4t_lds(L + wMT, p0 + fr, q0 + 4 * fq, mn); } }
;         LBAR();
;     }
	ds_read_b64 v[242:243], v127 offset:18432
	ds_read_b128 v[176:179], v173 offset:0
	ds_read_b128 v[224:227], v107 offset:18432
	ds_read_b64_tr_b16 v[184:185], v252 offset:0
	ds_read_b64_tr_b16 v[186:187], v252 offset:576
	ds_read_b128 v[232:235], v107 offset:0
	ds_read_b64_tr_b16 v[192:193], v252 offset:32
	ds_read_b64_tr_b16 v[194:195], v252 offset:608
	ds_read_b128 v[180:183], v173 offset:64
	ds_read_b128 v[228:231], v107 offset:18496
	ds_read_b64_tr_b16 v[188:189], v252 offset:4608
	ds_read_b64_tr_b16 v[190:191], v252 offset:5184
	ds_read_b128 v[236:239], v107 offset:64
	ds_read_b64_tr_b16 v[196:197], v252 offset:4640
	ds_read_b64_tr_b16 v[198:199], v252 offset:5216
	s_waitcnt lgkmcnt(14)
	v_lshlrev_b32_e32 v240, 16, v242
	v_and_b32_e32 v241, 0xffff0000, v242
	v_lshlrev_b32_e32 v242, 16, v243
	v_and_b32_e32 v243, 0xffff0000, v243
	s_nop 1
	s_waitcnt lgkmcnt(12)
	v_mfma_f32_16x16x32_bf16 v[240:243], v[176:179], v[224:227], v[240:243]
	s_waitcnt lgkmcnt(9)
	v_mfma_f32_16x16x32_bf16 v[244:247], v[184:187], v[232:235], 0
	s_waitcnt lgkmcnt(7)
	v_mfma_f32_16x16x32_bf16 v[248:251], v[192:195], v[232:235], 0
	s_waitcnt lgkmcnt(5)
	v_mfma_f32_16x16x32_bf16 v[240:243], v[180:183], v[228:231], v[240:243]
	s_waitcnt lgkmcnt(2)
	v_mfma_f32_16x16x32_bf16 v[244:247], v[188:191], v[236:239], v[244:247]
	s_waitcnt lgkmcnt(0)
	v_mfma_f32_16x16x32_bf16 v[248:251], v[196:199], v[236:239], v[248:251]
	s_nop 7
	v_cvt_pk_bf16_f32 v176, v240, v241
	v_cvt_pk_bf16_f32 v177, v242, v243
	v_cvt_pk_bf16_f32 v184, v244, v245
	v_cvt_pk_bf16_f32 v185, v246, v247
	v_cvt_pk_bf16_f32 v192, v248, v249
	v_cvt_pk_bf16_f32 v193, v250, v251
	ds_write_b64 v97, v[176:177] offset:18432
	ds_write_b64 v97, v[184:185] offset:0
	ds_write_b64 v98, v[192:193] offset:0
	s_waitcnt lgkmcnt(0)
	s_barrier
	ds_read_b64 v[242:243], v97 offset:18432
	ds_read_b128 v[176:179], v175 offset:0
	ds_read_b128 v[224:227], v132 offset:18432
	ds_read_b64_tr_b16 v[184:185], v253 offset:0
	ds_read_b64_tr_b16 v[186:187], v253 offset:576
	ds_read_b128 v[232:235], v132 offset:0
	ds_read_b64_tr_b16 v[192:193], v253 offset:32
	ds_read_b64_tr_b16 v[194:195], v253 offset:608
	ds_read_b128 v[180:183], v175 offset:64
	ds_read_b128 v[228:231], v132 offset:18496
	ds_read_b64_tr_b16 v[188:189], v253 offset:4608
	ds_read_b64_tr_b16 v[190:191], v253 offset:5184
	ds_read_b128 v[236:239], v132 offset:64
	ds_read_b64_tr_b16 v[196:197], v253 offset:4640
	ds_read_b64_tr_b16 v[198:199], v253 offset:5216
	s_waitcnt lgkmcnt(14)
	v_lshlrev_b32_e32 v240, 16, v242
	v_and_b32_e32 v241, 0xffff0000, v242
	v_lshlrev_b32_e32 v242, 16, v243
	v_and_b32_e32 v243, 0xffff0000, v243
	s_nop 1
	s_waitcnt lgkmcnt(12)
	v_mfma_f32_16x16x32_bf16 v[240:243], v[176:179], v[224:227], v[240:243]
	s_waitcnt lgkmcnt(9)
	v_mfma_f32_16x16x32_bf16 v[244:247], v[184:187], v[232:235], 0
	s_waitcnt lgkmcnt(7)
	v_mfma_f32_16x16x32_bf16 v[248:251], v[192:195], v[232:235], 0
	s_waitcnt lgkmcnt(5)
	v_mfma_f32_16x16x32_bf16 v[240:243], v[180:183], v[228:231], v[240:243]
	s_waitcnt lgkmcnt(2)
	v_mfma_f32_16x16x32_bf16 v[244:247], v[188:191], v[236:239], v[244:247]
	s_waitcnt lgkmcnt(0)
	v_mfma_f32_16x16x32_bf16 v[248:251], v[196:199], v[236:239], v[248:251]
	s_nop 7
	v_cvt_pk_bf16_f32 v176, v240, v241
	v_cvt_pk_bf16_f32 v177, v242, v243
	v_cvt_pk_bf16_f32 v184, v244, v245
	v_cvt_pk_bf16_f32 v185, v246, v247
	v_cvt_pk_bf16_f32 v192, v248, v249
	v_cvt_pk_bf16_f32 v193, v250, v251
	ds_write_b64 v127, v[176:177] offset:18432
	ds_write_b64 v127, v[184:185] offset:0
	ds_write_b64 v129, v[192:193] offset:0
	s_waitcnt lgkmcnt(0)
	s_barrier
	ds_read_b64 v[242:243], v127 offset:18432
	ds_read_b128 v[176:179], v173 offset:0
	ds_read_b128 v[224:227], v107 offset:18432
	ds_read_b128 v[180:183], v173 offset:64
	ds_read_b128 v[228:231], v107 offset:18496
	s_waitcnt lgkmcnt(4)
	v_lshlrev_b32_e32 v240, 16, v242
	v_and_b32_e32 v241, 0xffff0000, v242
	v_lshlrev_b32_e32 v242, 16, v243
	v_and_b32_e32 v243, 0xffff0000, v243
	s_nop 1
	s_waitcnt lgkmcnt(2)
	v_mfma_f32_16x16x32_bf16 v[240:243], v[176:179], v[224:227], v[240:243]
	s_waitcnt lgkmcnt(0)
	v_mfma_f32_16x16x32_bf16 v[240:243], v[180:183], v[228:231], v[240:243]
	s_nop 7
	v_cvt_pk_bf16_f32 v176, v240, v241
	v_cvt_pk_bf16_f32 v177, v242, v243
	ds_write_b64 v97, v[176:177] offset:18432
	s_waitcnt lgkmcnt(0)
	s_barrier
	s_branch .La2_done
